# A6 forward substitution on all 8 waves (one column per 4 lanes, scalar f32 FMAs, L2 prefetch by one dummy load per thread) plus P3 epilogue rewrite
# baseline (speedup 1.0000x reference)
; #define LAS __attribute__((address_space(3)))
; __device__ __forceinline__ float sigmoidf_(float x) { return __builtin_amdgcn_rcpf(1.f + __expf(-x)); }
; __device__ __forceinline__ u32x2 pack4(float a, float b, float c, float d) { u32x2 o; o.x = pk2(a, b); o.y = pk2(c, d); return o; }
; __device__ __forceinline__ void chunkA_item(const Args& A, LAS unsigned char* lds, int tid, int lane, int wave, int ci, int ci_next, HeadConstA& H) {
;     ...
;         for (int nn = 0; nn < 2; ++nn) {
;             const int cl = (nth * 2 + nn) * 16 + fr;
;             f32x4 accw = {0.f, 0.f, 0.f, 0.f}, acca = {0.f, 0.f, 0.f, 0.f};
; #pragma unroll
;             for (int ks = 0; ks < 2; ++ks) { accw = MFMA16(ath[ks], H.bw[nn][ks], accw); acca = MFMA16(aad[ks], H.ba[nn][ks], acca); }
;             const float w0c = H.w0c[nn], a0c = H.a0c[nn];
; #pragma unroll
;             for (int jj = 0; jj < 4; ++jj) { const int t = mt * 16 + q4 * 4 + jj;
;                 ((LAS float*)(lds + CA_LW))[t * 64 + cl] = -0.6065306597126334f * sigmoidf_(w0c + accw[jj]);
;                 ((LAS float*)(lds + CA_AA))[t * 64 + cl] = sigmoidf_(a0c + acca[jj]); }
;     ...
;         for (int nt = 0; nt < 4; ++nt) {
;             const int t = nt * 16 + fr, s0 = ms * 16 + q4 * 4;
;             if (nt < ms) {
;                 *(LAS u32x2*)(O1 + t * 144 + s0 * 2) = (u32x2){0u, 0u};
;                 if (og == 1) *(LAS u32x2*)(lds + CA_NMRB + t * 144 + s0 * 2) = (u32x2){0u, 0u};
;             } else {
;                 f32x4 acc1 = {0.f, 0.f, 0.f, 0.f}, acc2 = {0.f, 0.f, 0.f, 0.f};
; #pragma unroll
;                 for (int ks = 0; ks < 2; ++ks) { const bf16x8 bb = ldsfrag(Bsrc, t, ks * 32 + q4 * 8); acc1 = MFMA16(aB[ks], bb, acc1); acc2 = MFMA16(aK[ks], bb, acc2); }
;                 float v1[4], v2[4];
; #pragma unroll
;                 for (int jj = 0; jj < 4; ++jj) { const int s = s0 + jj; const bool ok = og == 0 ? (s < t) : (s <= t); v1[jj] = ok ? acc1[jj] : 0.f; v2[jj] = ok ? acc2[jj] : 0.f; }
;                 *(LAS u32x2*)(O1 + t * 144 + s0 * 2) = pack4(v2[0], v2[1], v2[2], v2[3]);
;                 if (og == 0) {
; #pragma unroll
;                     for (int jj = 0; jj < 4; ++jj) ((LAS float*)(lds + CA_N))[t * 64 + jj * 16 + ms * 4 + q4] = v1[jj];
;                 } else *(LAS u32x2*)(lds + CA_NMRB + t * 144 + s0 * 2) = pack4(-v1[0], -v1[1], -v1[2], -v1[3]);
.LBB0_143:
	s_or_b64 exec, exec, s[4:5]
	s_add_u32 s4, s96, 0xd80000
	s_addc_u32 s5, s97, 0
	v_writelane_b32 v249, s4, 32
	v_lshrrev_b32_e32 v0, 2, v144
	v_lshlrev_b32_e32 v137, 2, v145
	v_writelane_b32 v249, s5, 33
	s_add_u32 s4, s96, 0xda0000
	s_addc_u32 s5, s97, 0
	v_writelane_b32 v249, s4, 34
	s_cmpk_gt_i32 s2, 0xfff
	v_and_b32_e32 v89, 48, v144
	v_cmp_eq_u32_e64 s[82:83], 0, v145
	v_or_b32_e32 v88, 48, v145
	v_writelane_b32 v249, s5, 35
	s_barrier
	s_cbranch_scc1 .LBB0_261
	v_mov_b32_e32 v73, 0
	v_readlane_b32 s4, v249, 32
	s_add_i32 s3, 0, 0x18800
	v_mov_b32_e32 v135, v73
	v_readlane_b32 s5, v249, 33
	v_readlane_b32 s10, v249, 3
	v_add_u32_e32 v79, s3, v137
	v_lshl_add_u64 v[74:75], s[4:5], 0, v[134:135]
	v_readlane_b32 s4, v249, 34
	s_lshl_b32 s3, s10, 3
	v_readlane_b32 s5, v249, 35
	s_and_b32 s91, s3, 0x1fffffe0
	v_lshlrev_b32_e32 v2, 5, v207
	v_lshl_add_u64 v[76:77], s[4:5], 0, v[134:135]
	s_or_b32 s4, s91, 16
	v_writelane_b32 v249, s4, 36
	v_or_b32_e32 v72, 0x1800, v2
	v_readlane_b32 s56, v249, 0
	s_bfe_u32 s13, s56, 0x20006
	s_lshl_b32 s5, s13, 4
	s_movk_i32 s4, 0x90
	v_lshl_add_u64 v[80:81], s[60:61], 0, v[72:73]
	v_or_b32_e32 v72, 0x1900, v2
	v_or_b32_e32 v2, s5, v132
	v_mad_u32_u24 v5, v2, s4, 0
	v_lshrrev_b32_e32 v2, 2, v145
	v_and_b32_e32 v2, 12, v2
	s_lshr_b32 s18, s56, 8
	v_or_b32_e32 v12, s5, v2
	v_lshl_or_b32 v6, s18, 5, v132
	v_lshlrev_b32_e32 v7, 6, v12
	v_add_lshl_u32 v8, v7, v6, 2
	s_add_i32 s6, 0, 0x10800
	s_add_i32 s7, 0, 0x14800
	v_add_u32_e32 v114, s6, v8
	v_add_u32_e32 v115, s7, v8
	v_or_b32_e32 v8, 64, v7
	v_add_lshl_u32 v9, v8, v6, 2
	v_add_u32_e32 v116, s6, v9
	v_add_u32_e32 v117, s7, v9
	v_or_b32_e32 v9, 0x80, v7
	v_add_lshl_u32 v10, v9, v6, 2
	v_add_u32_e32 v118, s6, v10
	v_add_u32_e32 v119, s7, v10
	v_or_b32_e32 v10, 0xc0, v7
	v_add_lshl_u32 v11, v10, v6, 2
	v_or_b32_e32 v6, 16, v6
	v_add_lshl_u32 v7, v7, v6, 2
	v_add_u32_e32 v122, s6, v7
	v_add_u32_e32 v123, s7, v7
	v_add_lshl_u32 v7, v8, v6, 2
	v_add_u32_e32 v124, s6, v7
	v_add_u32_e32 v125, s7, v7
	v_add_lshl_u32 v7, v9, v6, 2
	v_add_lshl_u32 v6, v10, v6, 2
	v_add_u32_e32 v135, s6, v6
	v_add_u32_e32 v139, s7, v6
	v_lshl_or_b32 v6, s10, 11, v137
	v_add_u32_e32 v126, s6, v7
	v_add_u32_e32 v127, s7, v7
	v_or_b32_e32 v7, 0x100, v6
	v_add_u32_e32 v149, s6, v7
	v_add_u32_e32 v150, s7, v7
	v_or_b32_e32 v7, 0x200, v6
	v_add_u32_e32 v151, s6, v7
	v_add_u32_e32 v152, s7, v7
	v_or_b32_e32 v7, 0x300, v6
	v_add_u32_e32 v153, s6, v7
	v_add_u32_e32 v154, s7, v7
	v_or_b32_e32 v7, 0x400, v6
	v_add_u32_e32 v155, s6, v7
	v_add_u32_e32 v156, s7, v7
	v_or_b32_e32 v7, 0x500, v6
	v_add_u32_e32 v141, s6, v6
	v_add_u32_e32 v143, 0, v6
	v_add_u32_e32 v148, s7, v6
	v_add_u32_e32 v157, s6, v7
	v_add_u32_e32 v158, s7, v7
	v_or_b32_e32 v7, 0x600, v6
	v_or_b32_e32 v6, 0x700, v6
	v_add_u32_e32 v120, s6, v11
	v_add_u32_e32 v159, s6, v7
	v_add_u32_e32 v161, s6, v6
	s_lshl_b32 s6, s10, 8
	s_cmp_lt_u32 s56, 64
	s_cselect_b64 s[14:15], -1, 0
	s_cmpk_gt_u32 s56, 0x7f
	v_add_u32_e32 v121, s7, v11
	v_add_u32_e32 v160, s7, v7
	v_add_u32_e32 v163, s7, v6
	v_writelane_b32 v249, s6, 37
	s_cselect_b64 s[6:7], -1, 0
	v_writelane_b32 v249, s6, 38
	s_cmpk_gt_u32 s56, 0xbf
	s_mov_b32 s11, 0x1d100
	v_writelane_b32 v249, s7, 39
	s_cselect_b64 s[6:7], -1, 0
	s_cmpk_gt_u32 s56, 0xff
	v_writelane_b32 v249, s6, 40
	s_cselect_b64 s[8:9], -1, 0
	s_cmpk_gt_u32 s56, 0x13f
	v_writelane_b32 v249, s7, 41
	s_cselect_b64 s[6:7], -1, 0
	v_writelane_b32 v249, s6, 42
	s_cmpk_gt_u32 s56, 0x17f
	v_lshlrev_b32_e32 v9, 1, v12
	v_writelane_b32 v249, s7, 43
	s_cselect_b64 s[6:7], -1, 0
	v_writelane_b32 v249, s6, 44
	s_cmpk_gt_u32 s56, 0x1bf
	v_cmp_le_u32_e64 s[20:21], v12, v132
	v_writelane_b32 v249, s7, 45
	s_cselect_b64 s[6:7], -1, 0
	v_writelane_b32 v249, s6, 46
	s_cmpk_gt_u32 s56, 0x1ff
	v_cndmask_b32_e64 v10, 0, 1, s[20:21]
	v_writelane_b32 v249, s7, 47
	s_cselect_b64 s[6:7], -1, 0
	v_writelane_b32 v249, s6, 48
	v_cmp_le_u32_e64 s[46:47], v12, v88
	s_movk_i32 s5, 0x100
	v_writelane_b32 v249, s7, 49
	s_add_u32 s6, s96, 0x1cb00000
	v_writelane_b32 v249, s6, 50
	s_addc_u32 s6, s97, 0
	v_writelane_b32 v249, s6, 51
	s_or_b32 s6, s3, 1
	s_mulk_i32 s6, 0x90
	s_lshl_b32 s12, s10, 5
	v_writelane_b32 v249, s6, 52
	s_lshl_b32 s79, s10, 4
	s_add_i32 s78, s12, 0
	s_add_i32 s6, 0, 0x19000
	s_cmpk_lt_u32 s56, 0x100
	s_cselect_b64 s[50:51], -1, 0
	s_and_b64 s[16:17], s[50:51], exec
	s_cselect_b32 s7, 0, 0x6c00
	s_cselect_b32 s11, s11, 0x21900
	s_add_i32 s7, s7, 0
	s_add_i32 s16, s11, 0
	s_add_i32 s11, 0, 0x19100
	s_add_i32 s17, s11, s79
	v_add_u32_e32 v166, s7, v89
	s_add_i32 s7, 0, 0x1f500
	s_cmp_eq_u32 s18, 1
	v_add_u32_e32 v7, s17, v2
	v_add_u32_e32 v167, s16, v9
	s_cselect_b64 s[16:17], -1, 0
	v_cmp_lt_u32_e64 s[18:19], v12, v132
	v_add_u32_e32 v168, s7, v9
	v_writelane_b32 v249, s16, 53
	s_cmp_lg_u32 s13, 0
	v_cndmask_b32_e64 v9, 0, 1, s[18:19]
	v_writelane_b32 v249, s17, 54
	s_cselect_b64 s[16:17], -1, 0
	v_cndmask_b32_e64 v9, v10, v9, s[50:51]
	v_writelane_b32 v249, s16, 55
	v_and_b32_e32 v9, 1, v9
	v_cndmask_b32_e64 v10, 0, 1, s[50:51]
	v_writelane_b32 v249, s17, 56
	v_cmp_eq_u32_e64 s[16:17], 1, v9
	v_or_b32_e32 v9, v2, v10
	s_cmp_lt_u32 s13, 2
	v_writelane_b32 v249, s16, 57
	v_add_u32_e32 v171, 0, v89
	s_movk_i32 s10, 0x110
	v_writelane_b32 v249, s17, 58
	v_cmp_gt_u32_e64 s[16:17], v132, v9
	v_or_b32_e32 v9, 2, v2
	v_cmp_lt_u32_e64 s[22:23], v9, v132
	v_cmp_le_u32_e64 s[24:25], v9, v132
	v_writelane_b32 v249, s16, 59
	v_cndmask_b32_e64 v9, 0, 1, s[22:23]
	v_cndmask_b32_e64 v11, 0, 1, s[24:25]
	v_cndmask_b32_e64 v9, v11, v9, s[50:51]
	v_and_b32_e32 v9, 1, v9
	v_writelane_b32 v249, s17, 60
	v_cmp_eq_u32_e64 s[16:17], 1, v9
; #define LAS __attribute__((address_space(3)))
; __device__ __forceinline__ u32x2 pack4(float a, float b, float c, float d) { u32x2 o; o.x = pk2(a, b); o.y = pk2(c, d); return o; }
; #define MFMA16(a, b, c) __builtin_amdgcn_mfma_f32_16x16x32_bf16(a, b, c, 0, 0, 0)
; __device__ __forceinline__ void chunkA_item(const Args& A, LAS unsigned char* lds, int tid, int lane, int wave, int ci, int ci_next, HeadConstA& H) {
;     ...
;         for (int nt = 0; nt < 4; ++nt) {
;             const int t = nt * 16 + fr, s0 = ms * 16 + q4 * 4;
;             if (nt < ms) {
;                 *(LAS u32x2*)(O1 + t * 144 + s0 * 2) = (u32x2){0u, 0u};
;                 if (og == 1) *(LAS u32x2*)(lds + CA_NMRB + t * 144 + s0 * 2) = (u32x2){0u, 0u};
;             } else {
;                 f32x4 acc1 = {0.f, 0.f, 0.f, 0.f}, acc2 = {0.f, 0.f, 0.f, 0.f};
; #pragma unroll
;                 for (int ks = 0; ks < 2; ++ks) { const bf16x8 bb = ldsfrag(Bsrc, t, ks * 32 + q4 * 8); acc1 = MFMA16(aB[ks], bb, acc1); acc2 = MFMA16(aK[ks], bb, acc2); }
;                 float v1[4], v2[4];
; #pragma unroll
;                 for (int jj = 0; jj < 4; ++jj) { const int s = s0 + jj; const bool ok = og == 0 ? (s < t) : (s <= t); v1[jj] = ok ? acc1[jj] : 0.f; v2[jj] = ok ? acc2[jj] : 0.f; }
;                 *(LAS u32x2*)(O1 + t * 144 + s0 * 2) = pack4(v2[0], v2[1], v2[2], v2[3]);
;                 if (og == 0) {
; #pragma unroll
;                     for (int jj = 0; jj < 4; ++jj) ((LAS float*)(lds + CA_N))[t * 64 + jj * 16 + ms * 4 + q4] = v1[jj];
;                 } else *(LAS u32x2*)(lds + CA_NMRB + t * 144 + s0 * 2) = pack4(-v1[0], -v1[1], -v1[2], -v1[3]);
	v_or_b32_e32 v9, 3, v2
	v_cmp_lt_u32_e64 s[24:25], v9, v132
	v_cmp_le_u32_e64 s[26:27], v9, v132
	v_writelane_b32 v249, s16, 61
	v_cndmask_b32_e64 v9, 0, 1, s[24:25]
	v_cndmask_b32_e64 v11, 0, 1, s[26:27]
	v_cndmask_b32_e64 v9, v11, v9, s[50:51]
	v_and_b32_e32 v9, 1, v9
	v_or_b32_e32 v11, 16, v132
	v_writelane_b32 v249, s17, 62
	v_cmp_eq_u32_e64 s[16:17], 1, v9
	v_cmp_lt_u32_e64 s[26:27], v12, v11
	v_cmp_le_u32_e64 s[28:29], v12, v11
	v_writelane_b32 v249, s16, 63
	v_cndmask_b32_e64 v13, 0, 1, s[26:27]
	v_cndmask_b32_e64 v14, 0, 1, s[28:29]
	v_writelane_b32 v248, s17, 0
	s_cselect_b64 s[16:17], -1, 0
	v_cndmask_b32_e64 v13, v14, v13, s[50:51]
	v_writelane_b32 v248, s16, 1
	v_and_b32_e32 v13, 1, v13
	v_or_b32_e32 v14, 2, v12
	v_writelane_b32 v248, s17, 2
	v_cmp_eq_u32_e64 s[16:17], 1, v13
	v_cmp_lt_u32_e64 s[30:31], v14, v11
	v_cmp_le_u32_e64 s[34:35], v14, v11
	v_writelane_b32 v248, s16, 3
	v_or_b32_e32 v13, v12, v10
	v_cndmask_b32_e64 v10, 0, 1, s[30:31]
	v_cndmask_b32_e64 v15, 0, 1, s[34:35]
	v_writelane_b32 v248, s17, 4
	v_cmp_gt_u32_e64 s[16:17], v11, v13
	v_cndmask_b32_e64 v10, v15, v10, s[50:51]
	v_or_b32_e32 v15, 3, v12
	v_writelane_b32 v248, s16, 5
	v_and_b32_e32 v10, 1, v10
	v_cmp_lt_u32_e64 s[34:35], v15, v11
	v_cmp_le_u32_e64 s[36:37], v15, v11
	v_writelane_b32 v248, s17, 6
	v_cmp_eq_u32_e64 s[16:17], 1, v10
	v_cndmask_b32_e64 v10, 0, 1, s[34:35]
	v_cndmask_b32_e64 v16, 0, 1, s[36:37]
	v_cndmask_b32_e64 v10, v16, v10, s[50:51]
	v_writelane_b32 v248, s16, 7
	v_and_b32_e32 v10, 1, v10
	s_cmp_lg_u32 s13, 3
	v_writelane_b32 v248, s17, 8
	v_cmp_eq_u32_e64 s[16:17], 1, v10
	v_lshlrev_b32_e32 v10, 8, v11
	v_or_b32_e32 v11, 32, v132
	v_cmp_lt_u32_e64 s[36:37], v12, v11
	v_cmp_le_u32_e64 s[38:39], v12, v11
	v_writelane_b32 v248, s16, 9
	v_cndmask_b32_e64 v16, 0, 1, s[36:37]
	v_cndmask_b32_e64 v17, 0, 1, s[38:39]
	v_writelane_b32 v248, s17, 10
	s_cselect_b64 s[16:17], -1, 0
	v_cndmask_b32_e64 v16, v17, v16, s[50:51]
	v_writelane_b32 v248, s16, 11
	v_and_b32_e32 v16, 1, v16
	v_cmp_lt_u32_e64 s[40:41], v14, v11
	v_writelane_b32 v248, s17, 12
	v_cmp_eq_u32_e64 s[16:17], 1, v16
	v_cmp_le_u32_e64 s[42:43], v14, v11
	v_cndmask_b32_e64 v16, 0, 1, s[40:41]
	v_writelane_b32 v248, s16, 13
	v_cndmask_b32_e64 v17, 0, 1, s[42:43]
	v_cndmask_b32_e64 v16, v17, v16, s[50:51]
	v_writelane_b32 v248, s17, 14
	v_cmp_gt_u32_e64 s[16:17], v11, v13
	v_and_b32_e32 v16, 1, v16
	v_cmp_lt_u32_e64 s[42:43], v15, v11
	v_writelane_b32 v248, s16, 15
	v_cmp_le_u32_e64 s[44:45], v15, v11
	v_cmp_lt_u32_e64 s[48:49], v14, v88
	v_writelane_b32 v248, s17, 16
	v_cmp_eq_u32_e64 s[16:17], 1, v16
	v_cndmask_b32_e64 v16, 0, 1, s[42:43]
	v_cndmask_b32_e64 v17, 0, 1, s[44:45]
	v_cndmask_b32_e64 v16, v17, v16, s[50:51]
	v_writelane_b32 v248, s16, 17
	v_and_b32_e32 v16, 1, v16
	v_cmp_lt_u32_e64 s[44:45], v12, v88
	v_writelane_b32 v248, s17, 18
	v_cmp_eq_u32_e64 s[16:17], 1, v16
	v_cndmask_b32_e64 v12, 0, 1, s[44:45]
	v_cndmask_b32_e64 v16, 0, 1, s[46:47]
	v_cndmask_b32_e64 v12, v16, v12, s[50:51]
	v_and_b32_e32 v12, 1, v12
	v_cmp_le_u32_e64 s[52:53], v14, v88
	v_cmp_eq_u32_e64 s[44:45], 1, v12
	v_cmp_gt_u32_e64 s[46:47], v88, v13
	v_cndmask_b32_e64 v12, 0, 1, s[48:49]
	v_cndmask_b32_e64 v13, 0, 1, s[52:53]
	v_cndmask_b32_e64 v12, v13, v12, s[50:51]
	v_writelane_b32 v248, s16, 19
	v_and_b32_e32 v12, 1, v12
	v_cmp_lt_u32_e64 s[52:53], v15, v88
	v_cmp_le_u32_e64 s[54:55], v15, v88
	s_lshr_b32 s13, s56, 7
	v_and_or_b32 v15, s12, 32, v132
	v_writelane_b32 v248, s17, 20
	v_cmp_eq_u32_e64 s[48:49], 1, v12
	v_cndmask_b32_e64 v12, 0, 1, s[52:53]
	s_lshl_b32 s16, s13, 4
	s_lshl_b32 s13, s13, 6
	v_mul_u32_u24_e32 v16, 0x110, v15
	v_subrev_co_u32_e64 v175, s[52:53], s5, v144
	v_add3_u32 v16, v171, s13, v16
	s_xor_b64 s[12:13], s[52:53], -1
	v_writelane_b32 v248, s12, 21
	s_movk_i32 s5, 0x245
	s_add_i32 s17, 0, 0x1d100
	v_writelane_b32 v248, s13, 22
	v_cmp_gt_u32_e64 s[12:13], s5, v144
	s_add_u32 s5, s96, 0x18b00000
	v_cndmask_b32_e64 v13, 0, 1, s[54:55]
	v_writelane_b32 v248, s12, 23
	v_mad_u32_u24 v177, v0, s10, 0
	v_lshlrev_b32_e32 v0, 7, v0
	v_writelane_b32 v248, s13, 24
	v_writelane_b32 v248, s5, 25
; #define LAS __attribute__((address_space(3)))
; #define MFMA16(a, b, c) __builtin_amdgcn_mfma_f32_16x16x32_bf16(a, b, c, 0, 0, 0)
; __device__ __forceinline__ void chunkA_item(const Args& A, LAS unsigned char* lds, int tid, int lane, int wave, int ci, int ci_next, HeadConstA& H) {
;     ...
;         const int og = wave >> 2, ms = wave & 3;
;         const LAS unsigned char* Bsrc = lds + (og == 0 ? CA_KKT : CA_RT);
;         bf16x8 aB[2], aK[2];
; #pragma unroll
;         for (int ks = 0; ks < 2; ++ks) { aB[ks] = ldsfrag(lds + CA_BT, ms * 16 + fr, ks * 32 + q4 * 8); aK[ks] = ldsfrag(lds + CA_KT, ms * 16 + fr, ks * 32 + q4 * 8); }
;         LAS unsigned char* O1 = lds + (og == 0 ? CA_MAK : CA_MRK);
; #pragma unroll
;         for (int nt = 0; nt < 4; ++nt) {
;             const int t = nt * 16 + fr, s0 = ms * 16 + q4 * 4;
;             if (nt < ms) {
;                 *(LAS u32x2*)(O1 + t * 144 + s0 * 2) = (u32x2){0u, 0u};
;                 if (og == 1) *(LAS u32x2*)(lds + CA_NMRB + t * 144 + s0 * 2) = (u32x2){0u, 0u};
;             } else {
;                 f32x4 acc1 = {0.f, 0.f, 0.f, 0.f}, acc2 = {0.f, 0.f, 0.f, 0.f};
; #pragma unroll
;                 for (int ks = 0; ks < 2; ++ks) { const bf16x8 bb = ldsfrag(Bsrc, t, ks * 32 + q4 * 8); acc1 = MFMA16(aB[ks], bb, acc1); acc2 = MFMA16(aK[ks], bb, acc2); }
;                 float v1[4], v2[4];
; #pragma unroll
;                 for (int jj = 0; jj < 4; ++jj) { const int s = s0 + jj; const bool ok = og == 0 ? (s < t) : (s <= t); v1[jj] = ok ? acc1[jj] : 0.f; v2[jj] = ok ? acc2[jj] : 0.f; }
;                 *(LAS u32x2*)(O1 + t * 144 + s0 * 2) = pack4(v2[0], v2[1], v2[2], v2[3]);
;                 if (og == 0) {
; #pragma unroll
;                     for (int jj = 0; jj < 4; ++jj) ((LAS float*)(lds + CA_N))[t * 64 + jj * 16 + ms * 4 + q4] = v1[jj];
;                 } else *(LAS u32x2*)(lds + CA_NMRB + t * 144 + s0 * 2) = pack4(-v1[0], -v1[1], -v1[2], -v1[3]);
;             }
;         }
;     }
;     ...
;         const int cn = ci_next & 31, hn = (ci_next >> 5) & 7, bn = ci_next >> 8; const long rown = (long)bn * SEQ + cn * 64 - 1;
;         for (int l = tid - 256; l < 65 * 5; l += 256) { const int r = l / 5, sec = l % 5; long rr = rown + r; if (rr < 0) rr = 0;
;             const bf16_t* p = Z + rr * NZ + (sec == 0 ? hn * 64 : sec == 1 ? 512 + hn * 64 : sec == 2 ? 1024 + hn * 64 : sec == 3 ? 1536 : 1600);
	s_addc_u32 s43, s97, 0
	s_add_i32 s5, s16, 64
	v_cndmask_b32_e64 v12, v13, v12, s[50:51]
	v_sub_u32_e32 v19, 0, v0
	v_or_b32_e32 v0, s5, v132
	v_and_b32_e32 v12, 1, v12
	v_mul_lo_u32 v0, v0, s4
	v_cmp_eq_u32_e64 s[50:51], 1, v12
	v_or_b32_e32 v12, s16, v132
	v_add_u32_e32 v20, 0, v0
	v_or_b32_e32 v0, s16, v2
	v_mul_lo_u32 v12, v12, s4
	v_add_u32_e32 v173, 0xfc00, v16
	v_mov_b32_e32 v18, 0x900
	v_add_u32_e32 v174, 0x10d00, v16
	v_and_b32_e32 v16, 3, v144
	v_mov_b32_e32 v2, s7
	s_add_i32 s12, 0, 0x21900
	v_lshlrev_b32_e32 v27, 6, v0
	v_add_u32_e32 v14, s17, v12
	v_or_b32_e32 v17, 16, v15
	v_mad_u32_u24 v18, v15, s4, v18
	v_lshl_add_u32 v176, v16, 6, s11
	v_cmp_eq_u32_e64 s[54:55], 0, v16
	v_cmp_eq_u32_e64 s[56:57], 1, v16
	v_cmp_eq_u32_e64 s[58:59], 2, v16
	v_cmp_eq_u32_e64 s[64:65], 3, v16
	v_add_u32_e32 v16, 0, v12
	v_or_b32_e32 v12, 1, v0
	v_or_b32_e32 v21, 3, v0
	v_or_b32_e32 v22, 2, v0
	v_mad_u32_u24 v25, v15, s4, v2
	v_mov_b32_e32 v2, s12
	v_or_b32_e32 v28, 64, v27
	v_or_b32_e32 v29, 0x80, v27
	v_or_b32_e32 v30, 0xc0, v27
	v_cmp_gt_u32_e32 vcc, 8, v144
	v_mad_u32_u24 v1, v147, s4, 0
	v_lshlrev_b32_e32 v3, 4, v207
	v_lshlrev_b32_e32 v4, 5, v144
	v_mad_u32_u24 v8, v145, s4, 0
	v_mul_u32_u24_e32 v6, 0x110, v145
	v_lshlrev_b32_e32 v9, 8, v132
	v_lshlrev_b32_e32 v11, 8, v11
	v_lshlrev_b32_e32 v13, 8, v88
	v_mul_u32_u24_e32 v172, 0x90, v15
	v_lshl_add_u32 v23, v0, 1, 0
	v_mad_u32_u24 v24, v15, s4, 0
	v_mad_u32_u24 v26, v15, s4, v2
	v_lshl_add_u32 v179, v15, 2, s6
	v_cmp_eq_u32_e64 s[20:21], v0, v15
	v_cmp_eq_u32_e64 s[10:11], v12, v15
	v_cmp_eq_u32_e64 s[52:53], v21, v15
	v_cmp_eq_u32_e64 s[4:5], v22, v15
	v_lshlrev_b32_e32 v2, 6, v15
	v_or_b32_e32 v84, v27, v15
	v_or_b32_e32 v86, v28, v15
	v_or_b32_e32 v90, v29, v15
	v_or_b32_e32 v92, v30, v15
	v_add_u32_e32 v15, 0, v18
	v_add_u32_e32 v31, s7, v18
	v_add_u32_e32 v18, s12, v18
	v_cmp_eq_u32_e64 s[12:13], v12, v17
	v_lshlrev_b32_e32 v12, 6, v17
	v_lshlrev_b32_e32 v78, 3, v207
	v_lshl_add_u64 v[82:83], s[60:61], 0, v[72:73]
	v_lshl_add_u32 v164, v145, 1, 0
	v_add_u32_e32 v165, s6, v137
	v_mul_u32_u24_e32 v169, 0x90, v132
	v_mul_u32_u24_e32 v170, 0x90, v88
	v_add_u32_e32 v178, 0xfc00, v177
	v_mov_b32_e32 v85, v73
	v_mov_b32_e32 v87, v73
	v_mov_b32_e32 v91, v73
	v_mov_b32_e32 v93, v73
	v_lshl_add_u32 v180, v17, 2, s6
	v_cmp_eq_u32_e64 s[6:7], v0, v17
	v_cmp_eq_u32_e64 s[16:17], v21, v17
	v_cmp_eq_u32_e64 s[18:19], v22, v17
	v_or_b32_e32 v94, v17, v27
	v_mov_b32_e32 v95, v73
	v_or_b32_e32 v96, v28, v17
	v_mov_b32_e32 v97, v73
	v_or_b32_e32 v98, v29, v17
	v_mov_b32_e32 v99, v73
	v_or_b32_e32 v100, v30, v17
	v_mov_b32_e32 v101, v73
	s_mov_b32 s29, -1
	s_xor_b64 s[26:27], vcc, -1
	s_movk_i32 s22, 0x1c00
	v_add_u32_e32 v181, s79, v8
	v_add_u32_e32 v182, s78, v6
	v_bfe_u32 v183, v144, 4, 4
	v_lshlrev_b32_e32 v183, 10, v183
	v_and_b32_e32 v184, 3, v144
	v_lshl_add_u32 v183, v184, 6, v183
	v_bfe_u32 v184, v144, 2, 2
	v_lshl_add_u32 v183, v184, 2, v183
	v_add_u32_e32 v183, 0x19100, v183
	v_mul_u32_u24_e32 v186, 0xcccd, v144
	v_lshrrev_b32_e32 v186, 18, v186
	v_mul_u32_u24_e32 v184, 0x1c00, v186
	v_mul_u32_u24_e32 v185, 5, v186
	v_sub_u32_e32 v185, v144, v185
	v_min_u32_e32 v186, 3, v185
	v_lshl_add_u32 v184, v186, 10, v184
	v_cmp_eq_u32_e32 vcc, 4, v185
	v_mov_b32_e32 v186, 0x80
	s_nop 0
	v_cndmask_b32_e32 v186, 0, v186, vcc
	v_add_u32_e32 v184, v184, v186
	v_cmp_gt_u32_e32 vcc, 3, v185
	v_mov_b32_e32 v185, 0x80
	s_nop 0
	v_cndmask_b32_e32 v185, 0, v185, vcc
	v_add_u32_e32 v187, v14, v89
	v_add_u32_e32 v188, v16, v89
	v_add_u32_e32 v189, v20, v89
	v_lshlrev_b32_e32 v102, 1, v0
	v_add_u32_e32 v190, v24, v89
	v_add_u32_e32 v191, v25, v89
	v_add_u32_e32 v192, v26, v89
	v_lshlrev_b32_e32 v104, 1, v2
	v_add_u32_e32 v193, v23, v172
	v_add_u32_e32 v194, v15, v89
	v_add_u32_e32 v195, v31, v89
	v_add_u32_e32 v196, v18, v89
	v_lshlrev_b32_e32 v106, 1, v12
	v_add_u32_e32 v197, 0, v4
	v_add_u32_e32 v198, v1, v3
	v_add_u32_e32 v199, v5, v89
	v_mov_b32_e32 v224, v73
	v_mov_b32_e32 v225, v73
	v_mov_b32_e32 v200, 0x640
	v_mov_b32_e32 v201, 0x600
	v_add_u32_e32 v202, v177, v19
	s_mov_b32 s28, s2
	s_branch .LBB0_147

; #define LAS __attribute__((address_space(3)))
; __device__ __forceinline__ void unpack8(u32x4 u, float* f) { f[0] = bflo(u.x); f[1] = bfhi(u.x); f[2] = bflo(u.y); f[3] = bfhi(u.y); f[4] = bflo(u.z); f[5] = bfhi(u.z); f[6] = bflo(u.w); f[7] = bfhi(u.w); }
; __device__ __forceinline__ void chunkA_item(const Args& A, LAS unsigned char* lds, int tid, int lane, int wave, int ci, int ci_next, HeadConstA& H) {
;     ...
;     {
;         const int t = tid >> 3, part = tid & 7; const bool first = (c == 0 && t == 0);
;         const bf16_t* zr = Z + (row0 + t) * NZ; const bf16_t* zp = zr - NZ;
; #pragma unroll
;         for (int s = 0; s < 5; ++s) {
;             const int zcol = (s == 0 ? h * 64 : s == 1 ? 512 + h * 64 : s == 2 ? 1024 + h * 64 : s == 3 ? 1536 : 1600) + part * 8;
;             const u32x4 cu = *(const u32x4*)(zr + zcol); u32x4 pu = {0u, 0u, 0u, 0u}; if (!first) pu = *(const u32x4*)(zp + zcol);
;             const f32x4 m0 = *(const f32x4*)(A.mu + zcol), m1 = *(const f32x4*)(A.mu + zcol + 4);
;             float cur[8], prv[8], o[8]; unpack8(cu, cur); unpack8(pu, prv);
;             const float mu[8] = {m0.x, m0.y, m0.z, m0.w, m1.x, m1.y, m1.z, m1.w};
; #pragma unroll
;             for (int i = 0; i < 8; ++i) o[i] = cur[i] + mu[i] * (prv[i] - cur[i]);
;             if (s < 3) { LAS f32x4* dst = (LAS f32x4*)(lds + s * 16384 + (t * 64 + part * 8) * 4); dst[0] = (f32x4){o[0], o[1], o[2], o[3]}; dst[1] = (f32x4){o[4], o[5], o[6], o[7]}; }
.LBB0_151:
	s_ashr_i32 s24, s28, 8
	s_and_b32 s29, s28, 31
	s_ashr_i32 s25, s24, 31
	s_lshl_b64 s[24:25], s[24:25], 11
	v_lshl_add_u32 v72, s29, 6, v147
	v_lshl_add_u64 v[108:109], s[24:25], 0, v[72:73]
	v_mov_b64_e32 v[110:111], s[94:95]
	v_mad_u64_u32 v[222:223], s[24:25], v108, s22, v[110:111]
	v_mad_i32_i24 v223, v109, s22, v223
	v_or_b32_e32 v72, s30, v78
	v_lshl_add_u64 v[108:109], v[72:73], 1, v[222:223]
	global_load_dwordx4 v[32:35], v[108:109], off
	global_load_dwordx4 v[36:39], v[108:109], off offset:1024
	global_load_dwordx4 v[40:43], v[108:109], off offset:2048
	v_lshl_add_u64 v[112:113], v[72:73], 2, s[60:61]
	v_lshlrev_b32_e32 v72, 1, v78
	v_lshl_add_u64 v[110:111], v[222:223], 0, v[72:73]
	global_load_dwordx4 v[44:47], v[110:111], off offset:3072
	global_load_dwordx4 v[48:51], v[110:111], off offset:3200
	s_cmp_lg_u32 s29, 0
	s_cselect_b64 s[24:25], -1, 0
	s_or_b64 s[78:79], s[24:25], s[26:27]
	s_movk_i32 s24, 0xe400
	s_mov_b32 s25, -1
	v_lshl_add_u64 v[108:109], v[108:109], 0, s[24:25]
	v_mov_b32_e32 v52, 0
	v_mov_b32_e32 v53, 0
	v_mov_b32_e32 v54, 0
	v_mov_b32_e32 v55, 0
	v_mov_b32_e32 v56, 0
	v_mov_b32_e32 v57, 0
	v_mov_b32_e32 v58, 0
	v_mov_b32_e32 v59, 0
	v_mov_b32_e32 v60, 0
	v_mov_b32_e32 v61, 0
	v_mov_b32_e32 v62, 0
	v_mov_b32_e32 v63, 0
	v_mov_b32_e32 v64, 0
	v_mov_b32_e32 v65, 0
	v_mov_b32_e32 v66, 0
	v_mov_b32_e32 v67, 0
	v_mov_b32_e32 v68, 0
	v_mov_b32_e32 v69, 0
	v_mov_b32_e32 v70, 0
	v_mov_b32_e32 v71, 0
	s_and_saveexec_b64 s[24:25], s[78:79]
	global_load_dwordx4 v[52:55], v[108:109], off
	global_load_dwordx4 v[56:59], v[108:109], off offset:1024
	global_load_dwordx4 v[60:63], v[108:109], off offset:2048
	global_load_dwordx4 v[64:67], v[110:111], off offset:-4096
	global_load_dwordx4 v[68:71], v[110:111], off offset:-3968
	s_or_b64 exec, exec, s[24:25]
	global_load_dwordx4 v[214:217], v[112:113], off
	global_load_dwordx4 v[218:221], v[112:113], off offset:16
	global_load_dwordx4 v[226:229], v[112:113], off offset:2048
	global_load_dwordx4 v[230:233], v[112:113], off offset:2064
	s_waitcnt vmcnt(2)
	v_lshlrev_b32_e32 v108, 16, v32
	v_and_b32_e32 v109, 0xffff0000, v32
	v_lshlrev_b32_e32 v110, 16, v33
	v_and_b32_e32 v111, 0xffff0000, v33
	v_lshlrev_b32_e32 v112, 16, v52
	v_and_b32_e32 v113, 0xffff0000, v52
	v_lshlrev_b32_e32 v250, 16, v53
	v_and_b32_e32 v251, 0xffff0000, v53
	v_lshlrev_b32_e32 v252, 16, v34
	v_and_b32_e32 v253, 0xffff0000, v34
	v_lshlrev_b32_e32 v254, 16, v35
	v_and_b32_e32 v255, 0xffff0000, v35
	v_lshlrev_b32_e32 v222, 16, v54
	v_and_b32_e32 v223, 0xffff0000, v54
	v_lshlrev_b32_e32 v32, 16, v55
	v_and_b32_e32 v33, 0xffff0000, v55
	v_pk_add_f32 v[112:113], v[112:113], v[108:109] neg_lo:[0,1] neg_hi:[0,1]
	v_pk_add_f32 v[250:251], v[250:251], v[110:111] neg_lo:[0,1] neg_hi:[0,1]
	v_pk_add_f32 v[222:223], v[222:223], v[252:253] neg_lo:[0,1] neg_hi:[0,1]
	v_pk_add_f32 v[32:33], v[32:33], v[254:255] neg_lo:[0,1] neg_hi:[0,1]
	v_pk_fma_f32 v[214:215], v[214:215], v[112:113], v[108:109]
	v_pk_fma_f32 v[216:217], v[216:217], v[250:251], v[110:111]
	v_pk_fma_f32 v[218:219], v[218:219], v[222:223], v[252:253]
	v_pk_fma_f32 v[220:221], v[220:221], v[32:33], v[254:255]
	ds_write_b128 v197, v[214:217] offset:0
	ds_write_b128 v197, v[218:221] offset:16
	v_or_b32_e32 v72, s30, v78
	v_or_b32_e32 v72, 0x400, v72
	v_lshl_add_u64 v[108:109], v[72:73], 2, s[60:61]
	global_load_dwordx4 v[214:217], v[108:109], off
	global_load_dwordx4 v[218:221], v[108:109], off offset:16
	s_waitcnt vmcnt(2)
	v_lshlrev_b32_e32 v108, 16, v36
	v_and_b32_e32 v109, 0xffff0000, v36
	v_lshlrev_b32_e32 v110, 16, v37
	v_and_b32_e32 v111, 0xffff0000, v37
	v_lshlrev_b32_e32 v112, 16, v56
	v_and_b32_e32 v113, 0xffff0000, v56
	v_lshlrev_b32_e32 v250, 16, v57
	v_and_b32_e32 v251, 0xffff0000, v57
	v_lshlrev_b32_e32 v252, 16, v38
	v_and_b32_e32 v253, 0xffff0000, v38
	v_lshlrev_b32_e32 v254, 16, v39
	v_and_b32_e32 v255, 0xffff0000, v39
	v_lshlrev_b32_e32 v222, 16, v58
	v_and_b32_e32 v223, 0xffff0000, v58
	v_lshlrev_b32_e32 v36, 16, v59
	v_and_b32_e32 v37, 0xffff0000, v59
	v_pk_add_f32 v[112:113], v[112:113], v[108:109] neg_lo:[0,1] neg_hi:[0,1]
	v_pk_add_f32 v[250:251], v[250:251], v[110:111] neg_lo:[0,1] neg_hi:[0,1]
	v_pk_add_f32 v[222:223], v[222:223], v[252:253] neg_lo:[0,1] neg_hi:[0,1]
	v_pk_add_f32 v[36:37], v[36:37], v[254:255] neg_lo:[0,1] neg_hi:[0,1]
	v_pk_fma_f32 v[226:227], v[226:227], v[112:113], v[108:109]
	v_pk_fma_f32 v[228:229], v[228:229], v[250:251], v[110:111]
	v_pk_fma_f32 v[230:231], v[230:231], v[222:223], v[252:253]
	v_pk_fma_f32 v[232:233], v[232:233], v[36:37], v[254:255]
	ds_write_b128 v197, v[226:229] offset:16384
	ds_write_b128 v197, v[230:233] offset:16400
	global_load_dwordx4 v[226:229], v[80:81], off
	global_load_dwordx4 v[230:233], v[80:81], off offset:16
	s_waitcnt vmcnt(2)
	v_lshlrev_b32_e32 v108, 16, v40
	v_and_b32_e32 v109, 0xffff0000, v40
	v_lshlrev_b32_e32 v110, 16, v41
	v_and_b32_e32 v111, 0xffff0000, v41
	v_lshlrev_b32_e32 v112, 16, v60
	v_and_b32_e32 v113, 0xffff0000, v60
	v_lshlrev_b32_e32 v250, 16, v61
	v_and_b32_e32 v251, 0xffff0000, v61
	v_lshlrev_b32_e32 v252, 16, v42
	v_and_b32_e32 v253, 0xffff0000, v42
	v_lshlrev_b32_e32 v254, 16, v43
	v_and_b32_e32 v255, 0xffff0000, v43
	v_lshlrev_b32_e32 v222, 16, v62
	v_and_b32_e32 v223, 0xffff0000, v62
	v_lshlrev_b32_e32 v40, 16, v63
	v_and_b32_e32 v41, 0xffff0000, v63
	v_pk_add_f32 v[112:113], v[112:113], v[108:109] neg_lo:[0,1] neg_hi:[0,1]
	v_pk_add_f32 v[250:251], v[250:251], v[110:111] neg_lo:[0,1] neg_hi:[0,1]
	v_pk_add_f32 v[222:223], v[222:223], v[252:253] neg_lo:[0,1] neg_hi:[0,1]
	v_pk_add_f32 v[40:41], v[40:41], v[254:255] neg_lo:[0,1] neg_hi:[0,1]
	v_pk_fma_f32 v[214:215], v[214:215], v[112:113], v[108:109]
	v_pk_fma_f32 v[216:217], v[216:217], v[250:251], v[110:111]
	v_pk_fma_f32 v[218:219], v[218:219], v[222:223], v[252:253]
	v_pk_fma_f32 v[220:221], v[220:221], v[40:41], v[254:255]
	ds_write_b128 v197, v[214:217] offset:32768
	ds_write_b128 v197, v[218:221] offset:32784
	global_load_dwordx4 v[214:217], v[82:83], off
	global_load_dwordx4 v[218:221], v[82:83], off offset:16
	s_waitcnt vmcnt(2)
; #define LAS __attribute__((address_space(3)))
; __device__ __forceinline__ void unpack8(u32x4 u, float* f) { f[0] = bflo(u.x); f[1] = bfhi(u.x); f[2] = bflo(u.y); f[3] = bfhi(u.y); f[4] = bflo(u.z); f[5] = bfhi(u.z); f[6] = bflo(u.w); f[7] = bfhi(u.w); }
; __device__ __forceinline__ u32x4 pack8(const float* f) { u32x4 o; o.x = pk2(f[0], f[1]); o.y = pk2(f[2], f[3]); o.z = pk2(f[4], f[5]); o.w = pk2(f[6], f[7]); return o; }
; #define LBAR() asm volatile("s_waitcnt lgkmcnt(0)\n\ts_barrier" ::: "memory")
; __device__ __forceinline__ void chunkA_item(const Args& A, LAS unsigned char* lds, int tid, int lane, int wave, int ci, int ci_next, HeadConstA& H) {
;     ...
;             float cur[8], prv[8], o[8]; unpack8(cu, cur); unpack8(pu, prv);
;             const float mu[8] = {m0.x, m0.y, m0.z, m0.w, m1.x, m1.y, m1.z, m1.w};
; #pragma unroll
;             for (int i = 0; i < 8; ++i) o[i] = cur[i] + mu[i] * (prv[i] - cur[i]);
;             if (s < 3) { LAS f32x4* dst = (LAS f32x4*)(lds + s * 16384 + (t * 64 + part * 8) * 4); dst[0] = (f32x4){o[0], o[1], o[2], o[3]}; dst[1] = (f32x4){o[4], o[5], o[6], o[7]}; }
;             else { if (s == 3) {
; #pragma unroll
;                     for (int i = 0; i < 8; ++i) o[i] = 1.f - 2.f * __builtin_amdgcn_rcpf(1.f + __expf(2.f * o[i])); }
;                 *(LAS u32x4*)(lds + (s == 3 ? CA_TH : CA_AD) + t * 144 + part * 16) = pack8(o); }
;         }
;     }
;     LBAR();
	v_lshlrev_b32_e32 v108, 16, v44
	v_and_b32_e32 v109, 0xffff0000, v44
	v_lshlrev_b32_e32 v110, 16, v45
	v_and_b32_e32 v111, 0xffff0000, v45
	v_lshlrev_b32_e32 v112, 16, v64
	v_and_b32_e32 v113, 0xffff0000, v64
	v_lshlrev_b32_e32 v250, 16, v65
	v_and_b32_e32 v251, 0xffff0000, v65
	v_lshlrev_b32_e32 v252, 16, v46
	v_and_b32_e32 v253, 0xffff0000, v46
	v_lshlrev_b32_e32 v254, 16, v47
	v_and_b32_e32 v255, 0xffff0000, v47
	v_lshlrev_b32_e32 v222, 16, v66
	v_and_b32_e32 v223, 0xffff0000, v66
	v_lshlrev_b32_e32 v44, 16, v67
	v_and_b32_e32 v45, 0xffff0000, v67
	v_pk_add_f32 v[112:113], v[112:113], v[108:109] neg_lo:[0,1] neg_hi:[0,1]
	v_pk_add_f32 v[250:251], v[250:251], v[110:111] neg_lo:[0,1] neg_hi:[0,1]
	v_pk_add_f32 v[222:223], v[222:223], v[252:253] neg_lo:[0,1] neg_hi:[0,1]
	v_pk_add_f32 v[44:45], v[44:45], v[254:255] neg_lo:[0,1] neg_hi:[0,1]
	v_pk_fma_f32 v[226:227], v[226:227], v[112:113], v[108:109]
	v_pk_fma_f32 v[228:229], v[228:229], v[250:251], v[110:111]
	v_pk_fma_f32 v[230:231], v[230:231], v[222:223], v[252:253]
	v_pk_fma_f32 v[232:233], v[232:233], v[44:45], v[254:255]
	v_add_f32_e32 v226, v226, v226
	v_add_f32_e32 v227, v227, v227
	v_add_f32_e32 v228, v228, v228
	v_add_f32_e32 v229, v229, v229
	v_add_f32_e32 v230, v230, v230
	v_add_f32_e32 v231, v231, v231
	v_add_f32_e32 v232, v232, v232
	v_add_f32_e32 v233, v233, v233
	v_mul_f32_e32 v226, 0x3fb8aa3b, v226
	v_mul_f32_e32 v227, 0x3fb8aa3b, v227
	v_mul_f32_e32 v228, 0x3fb8aa3b, v228
	v_mul_f32_e32 v229, 0x3fb8aa3b, v229
	v_mul_f32_e32 v230, 0x3fb8aa3b, v230
	v_mul_f32_e32 v231, 0x3fb8aa3b, v231
	v_mul_f32_e32 v232, 0x3fb8aa3b, v232
	v_mul_f32_e32 v233, 0x3fb8aa3b, v233
	v_exp_f32_e32 v226, v226
	v_exp_f32_e32 v227, v227
	v_exp_f32_e32 v228, v228
	v_exp_f32_e32 v229, v229
	v_exp_f32_e32 v230, v230
	v_exp_f32_e32 v231, v231
	v_exp_f32_e32 v232, v232
	v_exp_f32_e32 v233, v233
	v_add_f32_e32 v226, 1.0, v226
	v_add_f32_e32 v227, 1.0, v227
	v_add_f32_e32 v228, 1.0, v228
	v_add_f32_e32 v229, 1.0, v229
	v_add_f32_e32 v230, 1.0, v230
	v_add_f32_e32 v231, 1.0, v231
	v_add_f32_e32 v232, 1.0, v232
	v_add_f32_e32 v233, 1.0, v233
	v_rcp_f32_e32 v226, v226
	v_rcp_f32_e32 v227, v227
	v_rcp_f32_e32 v228, v228
	v_rcp_f32_e32 v229, v229
	v_rcp_f32_e32 v230, v230
	v_rcp_f32_e32 v231, v231
	v_rcp_f32_e32 v232, v232
	v_rcp_f32_e32 v233, v233
	v_fma_f32 v226, -v226, 2.0, 1.0
	v_fma_f32 v227, -v227, 2.0, 1.0
	v_fma_f32 v228, -v228, 2.0, 1.0
	v_fma_f32 v229, -v229, 2.0, 1.0
	v_fma_f32 v230, -v230, 2.0, 1.0
	v_fma_f32 v231, -v231, 2.0, 1.0
	v_fma_f32 v232, -v232, 2.0, 1.0
	v_fma_f32 v233, -v233, 2.0, 1.0
	v_cvt_pk_bf16_f32 v226, v226, v227
	v_cvt_pk_bf16_f32 v227, v228, v229
	v_cvt_pk_bf16_f32 v228, v230, v231
	v_cvt_pk_bf16_f32 v229, v232, v233
	ds_write_b128 v198, v[226:229] offset:49152
	s_waitcnt vmcnt(0)
	v_lshlrev_b32_e32 v108, 16, v48
	v_and_b32_e32 v109, 0xffff0000, v48
	v_lshlrev_b32_e32 v110, 16, v49
	v_and_b32_e32 v111, 0xffff0000, v49
	v_lshlrev_b32_e32 v112, 16, v68
	v_and_b32_e32 v113, 0xffff0000, v68
	v_lshlrev_b32_e32 v250, 16, v69
	v_and_b32_e32 v251, 0xffff0000, v69
	v_lshlrev_b32_e32 v252, 16, v50
	v_and_b32_e32 v253, 0xffff0000, v50
	v_lshlrev_b32_e32 v254, 16, v51
	v_and_b32_e32 v255, 0xffff0000, v51
	v_lshlrev_b32_e32 v222, 16, v70
	v_and_b32_e32 v223, 0xffff0000, v70
	v_lshlrev_b32_e32 v48, 16, v71
	v_and_b32_e32 v49, 0xffff0000, v71
	v_pk_add_f32 v[112:113], v[112:113], v[108:109] neg_lo:[0,1] neg_hi:[0,1]
	v_pk_add_f32 v[250:251], v[250:251], v[110:111] neg_lo:[0,1] neg_hi:[0,1]
	v_pk_add_f32 v[222:223], v[222:223], v[252:253] neg_lo:[0,1] neg_hi:[0,1]
	v_pk_add_f32 v[48:49], v[48:49], v[254:255] neg_lo:[0,1] neg_hi:[0,1]
	v_pk_fma_f32 v[214:215], v[214:215], v[112:113], v[108:109]
	v_pk_fma_f32 v[216:217], v[216:217], v[250:251], v[110:111]
	v_pk_fma_f32 v[218:219], v[218:219], v[222:223], v[252:253]
	v_pk_fma_f32 v[220:221], v[220:221], v[48:49], v[254:255]
	v_cvt_pk_bf16_f32 v214, v214, v215
	v_cvt_pk_bf16_f32 v215, v216, v217
	v_cvt_pk_bf16_f32 v216, v218, v219
	v_cvt_pk_bf16_f32 v217, v220, v221
	ds_write_b128 v198, v[214:217] offset:58368
	v_mov_b32_e32 v69, v73
	v_readlane_b32 s24, v249, 37
	s_ashr_i32 s29, s28, 31
	v_readlane_b32 s30, v249, 50
	v_mov_b32_e32 v72, v73
	s_waitcnt lgkmcnt(0)
	s_barrier
; #define LAS __attribute__((address_space(3)))
; __device__ __forceinline__ float sigmoidf_(float x) { return __builtin_amdgcn_rcpf(1.f + __expf(-x)); }
; #define LBAR() asm volatile("s_waitcnt lgkmcnt(0)\n\ts_barrier" ::: "memory")
; #define MFMA16(a, b, c) __builtin_amdgcn_mfma_f32_16x16x32_bf16(a, b, c, 0, 0, 0)
; __device__ __forceinline__ void chunkA_item(const Args& A, LAS unsigned char* lds, int tid, int lane, int wave, int ci, int ci_next, HeadConstA& H) {
;     ...
;     {
;         const int mt = wave & 3, nth = wave >> 2;
;         bf16x8 ath[2], aad[2];
; #pragma unroll
;         for (int ks = 0; ks < 2; ++ks) { ath[ks] = ldsfrag(lds + CA_TH, mt * 16 + fr, ks * 32 + q4 * 8); aad[ks] = ldsfrag(lds + CA_AD, mt * 16 + fr, ks * 32 + q4 * 8); }
; #pragma unroll
;         for (int nn = 0; nn < 2; ++nn) {
;             const int cl = (nth * 2 + nn) * 16 + fr;
;             f32x4 accw = {0.f, 0.f, 0.f, 0.f}, acca = {0.f, 0.f, 0.f, 0.f};
; #pragma unroll
;             for (int ks = 0; ks < 2; ++ks) { accw = MFMA16(ath[ks], H.bw[nn][ks], accw); acca = MFMA16(aad[ks], H.ba[nn][ks], acca); }
;             const float w0c = H.w0c[nn], a0c = H.a0c[nn];
; #pragma unroll
;             for (int jj = 0; jj < 4; ++jj) { const int t = mt * 16 + q4 * 4 + jj;
;                 ((LAS float*)(lds + CA_LW))[t * 64 + cl] = -0.6065306597126334f * sigmoidf_(w0c + accw[jj]);
;                 ((LAS float*)(lds + CA_AA))[t * 64 + cl] = sigmoidf_(a0c + acca[jj]); }
;         }
;     }
;     LBAR();
;     {
;         const int cc = lane, seg = wave;
;         float lwv[8], pre[8], zr[8], zk[8], zv[8], av[8];
; #pragma unroll
;         for (int i = 0; i < 8; ++i) { const int t = seg * 8 + i; lwv[i] = ((LAS float*)(lds + CA_LW))[t * 64 + cc]; zr[i] = ((LAS float*)(lds + CA_ZR))[t * 64 + cc];
;             zk[i] = ((LAS float*)(lds + CA_ZK))[t * 64 + cc]; zv[i] = ((LAS float*)(lds + CA_ZV))[t * 64 + cc]; av[i] = ((LAS float*)(lds + CA_AA))[t * 64 + cc]; }
;         pre[0] = lwv[0];
; #pragma unroll
;         for (int i = 1; i < 8; ++i) pre[i] = pre[i - 1] + lwv[i];
;         ((LAS float*)(lds + CA_SEG))[seg * 64 + cc] = pre[7];
	ds_read_b128 v[32:35], v199 offset:49152
	ds_read_b128 v[36:39], v199 offset:49216
	ds_read_b128 v[44:47], v199 offset:58368
	ds_read_b128 v[48:51], v199 offset:58432
	s_waitcnt lgkmcnt(3)
	v_mfma_f32_16x16x32_bf16 v[40:43], v[32:35], v[0:3], 0
	v_mfma_f32_16x16x32_bf16 v[32:35], v[32:35], v[16:19], 0
	s_waitcnt lgkmcnt(1)
	v_mfma_f32_16x16x32_bf16 v[52:55], v[44:47], v[8:11], 0
	v_mfma_f32_16x16x32_bf16 v[40:43], v[36:39], v[4:7], v[40:43]
	v_mfma_f32_16x16x32_bf16 v[32:35], v[36:39], v[20:23], v[32:35]
	v_mfma_f32_16x16x32_bf16 v[44:47], v[44:47], v[24:27], 0
	s_nop 5
	v_add_f32_e32 v40, v203, v40
	v_add_f32_e32 v32, v208, v32
	v_add_f32_e32 v41, v203, v41
	s_waitcnt lgkmcnt(0)
	v_mfma_f32_16x16x32_bf16 v[52:55], v[48:51], v[12:15], v[52:55]
	v_add_f32_e32 v42, v203, v42
	v_add_f32_e32 v43, v203, v43
	v_add_f32_e32 v33, v208, v33
	v_mfma_f32_16x16x32_bf16 v[36:39], v[48:51], v[28:31], v[44:47]
	v_mul_f32_e32 v40, 0xbfb8aa3b, v40
	v_mul_f32_e32 v32, 0xbfb8aa3b, v32
	v_mul_f32_e32 v41, 0xbfb8aa3b, v41
	s_nop 0
	v_add_f32_e32 v44, v209, v52
	v_mul_f32_e32 v44, 0xbfb8aa3b, v44
	v_mul_f32_e32 v42, 0xbfb8aa3b, v42
	v_mul_f32_e32 v43, 0xbfb8aa3b, v43
	v_mul_f32_e32 v33, 0xbfb8aa3b, v33
	v_exp_f32_e32 v40, v40
	v_exp_f32_e32 v32, v32
	v_add_f32_e32 v45, v209, v53
	v_exp_f32_e32 v44, v44
	v_exp_f32_e32 v41, v41
	v_exp_f32_e32 v42, v42
	v_exp_f32_e32 v43, v43
	v_exp_f32_e32 v33, v33
	v_mul_f32_e32 v45, 0xbfb8aa3b, v45
	v_add_f32_e32 v46, v209, v54
	v_add_f32_e32 v47, v209, v55
	v_add_f32_e32 v36, v210, v36
	v_exp_f32_e32 v45, v45
	v_mul_f32_e32 v46, 0xbfb8aa3b, v46
	v_mul_f32_e32 v47, 0xbfb8aa3b, v47
	v_mul_f32_e32 v36, 0xbfb8aa3b, v36
	v_add_f32_e32 v40, 1.0, v40
	v_add_f32_e32 v32, 1.0, v32
	v_exp_f32_e32 v46, v46
	v_exp_f32_e32 v47, v47
	v_exp_f32_e32 v36, v36
	v_add_f32_e32 v44, 1.0, v44
	v_add_f32_e32 v41, 1.0, v41
	v_add_f32_e32 v42, 1.0, v42
	v_add_f32_e32 v43, 1.0, v43
	v_add_f32_e32 v33, 1.0, v33
	v_rcp_f32_e32 v40, v40
	v_rcp_f32_e32 v32, v32
	v_rcp_f32_e32 v44, v44
	v_rcp_f32_e32 v41, v41
	v_rcp_f32_e32 v42, v42
	v_rcp_f32_e32 v43, v43
	v_rcp_f32_e32 v33, v33
	v_add_f32_e32 v45, 1.0, v45
	v_rcp_f32_e32 v45, v45
	v_add_f32_e32 v46, 1.0, v46
	v_add_f32_e32 v47, 1.0, v47
	v_add_f32_e32 v36, 1.0, v36
	v_mul_f32_e32 v40, 0xbf1b4598, v40
	v_mul_f32_e32 v32, 0xbf1b4598, v32
	v_rcp_f32_e32 v46, v46
	v_rcp_f32_e32 v47, v47
	v_rcp_f32_e32 v36, v36
	ds_write_b32 v115, v44
	v_mul_f32_e32 v41, 0xbf1b4598, v41
	v_mul_f32_e32 v42, 0xbf1b4598, v42
	v_mul_f32_e32 v43, 0xbf1b4598, v43
	ds_write_b32 v114, v40
	ds_write_b32 v116, v41
	ds_write_b32 v117, v45
	ds_write_b32 v118, v42
	ds_write_b32 v119, v46
	ds_write_b32 v120, v43
	ds_write_b32 v121, v47
	ds_write_b32 v122, v32
	ds_write_b32 v123, v36
	v_mul_f32_e32 v32, 0xbf1b4598, v33
	v_add_f32_e32 v33, v210, v37
	v_add_f32_e32 v34, v208, v34
	v_mul_f32_e32 v33, 0xbfb8aa3b, v33
	v_mul_f32_e32 v34, 0xbfb8aa3b, v34
	v_exp_f32_e32 v33, v33
	v_exp_f32_e32 v34, v34
	ds_write_b32 v124, v32
	v_add_f32_e32 v32, 1.0, v33
	v_add_f32_e32 v33, 1.0, v34
	v_rcp_f32_e32 v32, v32
	v_rcp_f32_e32 v33, v33
	v_add_f32_e32 v34, v210, v38
	v_mul_f32_e32 v34, 0xbfb8aa3b, v34
	v_exp_f32_e32 v34, v34
	ds_write_b32 v125, v32
	v_mul_f32_e32 v32, 0xbf1b4598, v33
	v_add_f32_e32 v33, v208, v35
	v_mul_f32_e32 v33, 0xbfb8aa3b, v33
	ds_write_b32 v126, v32
	v_add_f32_e32 v32, 1.0, v34
	v_exp_f32_e32 v33, v33
	v_add_f32_e32 v34, v210, v39
	v_mul_f32_e32 v34, 0xbfb8aa3b, v34
	v_exp_f32_e32 v34, v34
	v_add_f32_e32 v33, 1.0, v33
	v_rcp_f32_e32 v32, v32
	v_rcp_f32_e32 v33, v33
	v_add_f32_e32 v34, 1.0, v34
	v_rcp_f32_e32 v34, v34
	ds_write_b32 v127, v32
	v_mul_f32_e32 v32, 0xbf1b4598, v33
	ds_write_b32 v135, v32
	ds_write_b32 v139, v34
	s_waitcnt lgkmcnt(0)
	s_barrier
	v_readlane_b32 s24, v249, 3
	ds_read2st64_b32 v[226:227], v141 offset0:0 offset1:1
	ds_read2st64_b32 v[228:229], v141 offset0:2 offset1:3
	ds_read2st64_b32 v[230:231], v141 offset0:4 offset1:5
	ds_read2st64_b32 v[232:233], v141 offset0:6 offset1:7
	ds_read2st64_b32 v[48:49], v143 offset0:64 offset1:65
	ds_read2st64_b32 v[50:51], v143 offset0:66 offset1:67
	ds_read2st64_b32 v[52:53], v143 offset0:68 offset1:69
	ds_read2st64_b32 v[54:55], v143 offset0:70 offset1:71
	ds_read2st64_b32 v[40:41], v141 offset0:64 offset1:65
	ds_read2st64_b32 v[42:43], v141 offset0:66 offset1:67
	ds_read2st64_b32 v[44:45], v141 offset0:68 offset1:69
	ds_read2st64_b32 v[46:47], v141 offset0:70 offset1:71
	ds_read2st64_b32 v[64:65], v143 offset0:0 offset1:1
	ds_read2st64_b32 v[66:67], v143 offset0:2 offset1:3
	ds_read2st64_b32 v[68:69], v143 offset0:4 offset1:5
	ds_read2st64_b32 v[70:71], v143 offset0:6 offset1:7
	ds_read2st64_b32 v[56:57], v143 offset0:128 offset1:129
	ds_read2st64_b32 v[58:59], v143 offset0:130 offset1:131
	ds_read2st64_b32 v[60:61], v143 offset0:132 offset1:133
	ds_read2st64_b32 v[62:63], v143 offset0:134 offset1:135
	v_readlane_b32 s25, v249, 37
	v_readlane_b32 s78, v249, 50
	v_readlane_b32 s79, v249, 51
	s_lshl_b32 s40, s28, 8
	s_add_u32 s78, s78, s40
	s_addc_u32 s79, s79, 0
	v_add_u32_e32 v107, s25, v79
	s_mul_i32 s25, s24, 0x480
	v_add_u32_e32 v103, s25, v164
	s_lshl_b32 s25, s3, 2
	v_mov_b32_e32 v105, s25
	s_mov_b32 s100, 0
	s_brev_b32 s101, 1
	s_waitcnt lgkmcnt(12)
	v_mov_b32_e32 v214, v226
	v_add_f32_e32 v215, v214, v227
	v_add_f32_e32 v216, v215, v228
	v_add_f32_e32 v217, v216, v229
	v_add_f32_e32 v218, v217, v230
	v_add_f32_e32 v219, v218, v231
	v_add_f32_e32 v220, v219, v232
	v_add_f32_e32 v221, v220, v233
	ds_write_b32 v107, v221
	s_waitcnt lgkmcnt(13)
; __device__ __forceinline__ void chunkA_item(const Args& A, LAS unsigned char* lds, int tid, int lane, int wave, int ci, int ci_next, HeadConstA& H) {
;     ...
;         const float kkc = H.kkc, kac = H.kac, rkc = H.rkc;
;         float rhs8[8], nbh8[8], kh8[8];
;         float* BCg = (float*)(A.ws + WS_BC) + (size_t)ci * 64;
; #pragma unroll
;         for (int i = 0; i < 8; ++i) { const int t = seg * 8 + i;
;             const float lg = off + pre[i], lgp = lg - lwv[i];
;             const float kkraw = zk[i] * kkc; const float n2 = wsum_fast(kkraw * kkraw); const float kk = kkraw * __builtin_amdgcn_rsqf(fmaxf(n2, 1e-24f));
;             const float a = av[i], bb = kk * a, km = zk[i] * (1.f + (a - 1.f) * kac);
	v_mul_f32_e32 v32, v211, v48
	v_mul_f32_e32 v33, v211, v49
	v_mul_f32_e32 v34, v211, v50
	v_mul_f32_e32 v35, v211, v51
	v_mul_f32_e32 v36, v211, v52
	v_mul_f32_e32 v37, v211, v53
	v_mul_f32_e32 v38, v211, v54
	v_mul_f32_e32 v39, v211, v55
	v_mul_f32_e32 v108, v32, v32
	v_mul_f32_e32 v109, v33, v33
	v_mul_f32_e32 v110, v34, v34
	v_mul_f32_e32 v111, v35, v35
	v_mul_f32_e32 v112, v36, v36
	v_mul_f32_e32 v113, v37, v37
	v_mul_f32_e32 v250, v38, v38
	v_mul_f32_e32 v251, v39, v39
	v_add_f32_dpp v108, v108, v108 quad_perm:[1,0,3,2] row_mask:0xf bank_mask:0xf
	v_add_f32_dpp v109, v109, v109 quad_perm:[1,0,3,2] row_mask:0xf bank_mask:0xf
	v_add_f32_dpp v110, v110, v110 quad_perm:[1,0,3,2] row_mask:0xf bank_mask:0xf
	v_add_f32_dpp v111, v111, v111 quad_perm:[1,0,3,2] row_mask:0xf bank_mask:0xf
	v_add_f32_dpp v112, v112, v112 quad_perm:[1,0,3,2] row_mask:0xf bank_mask:0xf
	v_add_f32_dpp v113, v113, v113 quad_perm:[1,0,3,2] row_mask:0xf bank_mask:0xf
	v_add_f32_dpp v250, v250, v250 quad_perm:[1,0,3,2] row_mask:0xf bank_mask:0xf
	v_add_f32_dpp v251, v251, v251 quad_perm:[1,0,3,2] row_mask:0xf bank_mask:0xf
	v_add_f32_dpp v108, v108, v108 quad_perm:[2,3,0,1] row_mask:0xf bank_mask:0xf
	v_add_f32_dpp v109, v109, v109 quad_perm:[2,3,0,1] row_mask:0xf bank_mask:0xf
	v_add_f32_dpp v110, v110, v110 quad_perm:[2,3,0,1] row_mask:0xf bank_mask:0xf
	v_add_f32_dpp v111, v111, v111 quad_perm:[2,3,0,1] row_mask:0xf bank_mask:0xf
	v_add_f32_dpp v112, v112, v112 quad_perm:[2,3,0,1] row_mask:0xf bank_mask:0xf
	v_add_f32_dpp v113, v113, v113 quad_perm:[2,3,0,1] row_mask:0xf bank_mask:0xf
	v_add_f32_dpp v250, v250, v250 quad_perm:[2,3,0,1] row_mask:0xf bank_mask:0xf
	v_add_f32_dpp v251, v251, v251 quad_perm:[2,3,0,1] row_mask:0xf bank_mask:0xf
	v_add_f32_dpp v108, v108, v108 row_half_mirror row_mask:0xf bank_mask:0xf
	v_add_f32_dpp v109, v109, v109 row_half_mirror row_mask:0xf bank_mask:0xf
	v_add_f32_dpp v110, v110, v110 row_half_mirror row_mask:0xf bank_mask:0xf
	v_add_f32_dpp v111, v111, v111 row_half_mirror row_mask:0xf bank_mask:0xf
	v_add_f32_dpp v112, v112, v112 row_half_mirror row_mask:0xf bank_mask:0xf
	v_add_f32_dpp v113, v113, v113 row_half_mirror row_mask:0xf bank_mask:0xf
	v_add_f32_dpp v250, v250, v250 row_half_mirror row_mask:0xf bank_mask:0xf
	v_add_f32_dpp v251, v251, v251 row_half_mirror row_mask:0xf bank_mask:0xf
	v_add_f32_dpp v108, v108, v108 row_mirror row_mask:0xf bank_mask:0xf
	v_add_f32_dpp v109, v109, v109 row_mirror row_mask:0xf bank_mask:0xf
	v_add_f32_dpp v110, v110, v110 row_mirror row_mask:0xf bank_mask:0xf
	v_add_f32_dpp v111, v111, v111 row_mirror row_mask:0xf bank_mask:0xf
	v_add_f32_dpp v112, v112, v112 row_mirror row_mask:0xf bank_mask:0xf
	v_add_f32_dpp v113, v113, v113 row_mirror row_mask:0xf bank_mask:0xf
	v_add_f32_dpp v250, v250, v250 row_mirror row_mask:0xf bank_mask:0xf
	v_add_f32_dpp v251, v251, v251 row_mirror row_mask:0xf bank_mask:0xf
	v_add_f32_dpp v108, v108, v108 row_bcast:15 row_mask:0xa bank_mask:0xf
	v_add_f32_dpp v109, v109, v109 row_bcast:15 row_mask:0xa bank_mask:0xf
	v_add_f32_dpp v110, v110, v110 row_bcast:15 row_mask:0xa bank_mask:0xf
	v_add_f32_dpp v111, v111, v111 row_bcast:15 row_mask:0xa bank_mask:0xf
	v_add_f32_dpp v112, v112, v112 row_bcast:15 row_mask:0xa bank_mask:0xf
	v_add_f32_dpp v113, v113, v113 row_bcast:15 row_mask:0xa bank_mask:0xf
	v_add_f32_dpp v250, v250, v250 row_bcast:15 row_mask:0xa bank_mask:0xf
	v_add_f32_dpp v251, v251, v251 row_bcast:15 row_mask:0xa bank_mask:0xf
	v_add_f32_dpp v108, v108, v108 row_bcast:31 row_mask:0xc bank_mask:0xf
	v_add_f32_dpp v109, v109, v109 row_bcast:31 row_mask:0xc bank_mask:0xf
	v_add_f32_dpp v110, v110, v110 row_bcast:31 row_mask:0xc bank_mask:0xf
	v_add_f32_dpp v111, v111, v111 row_bcast:31 row_mask:0xc bank_mask:0xf
	v_add_f32_dpp v112, v112, v112 row_bcast:31 row_mask:0xc bank_mask:0xf
	v_add_f32_dpp v113, v113, v113 row_bcast:31 row_mask:0xc bank_mask:0xf
	v_add_f32_dpp v250, v250, v250 row_bcast:31 row_mask:0xc bank_mask:0xf
	v_add_f32_dpp v251, v251, v251 row_bcast:31 row_mask:0xc bank_mask:0xf
	v_readlane_b32 s30, v108, 63
	v_readlane_b32 s31, v109, 63
	v_readlane_b32 s34, v110, 63
	v_readlane_b32 s35, v111, 63
	v_readlane_b32 s36, v112, 63
	v_readlane_b32 s37, v113, 63
	v_readlane_b32 s38, v250, 63
	v_readlane_b32 s39, v251, 63
	s_waitcnt lgkmcnt(9)
	v_add_f32_e32 v108, -1.0, v40
	v_add_f32_e32 v109, -1.0, v41
	v_add_f32_e32 v110, -1.0, v42
	v_add_f32_e32 v111, -1.0, v43
	v_add_f32_e32 v112, -1.0, v44
	v_add_f32_e32 v113, -1.0, v45
	v_add_f32_e32 v250, -1.0, v46
	v_add_f32_e32 v251, -1.0, v47
	v_fma_f32 v108, v212, v108, 1.0
	v_fma_f32 v109, v212, v109, 1.0
	v_fma_f32 v110, v212, v110, 1.0
	v_fma_f32 v111, v212, v111, 1.0
	v_fma_f32 v112, v212, v112, 1.0
	v_fma_f32 v113, v212, v113, 1.0
	v_fma_f32 v250, v212, v250, 1.0
	v_fma_f32 v251, v212, v251, 1.0
	v_mul_f32_e32 v48, v48, v108
	v_mul_f32_e32 v49, v49, v109
	v_mul_f32_e32 v50, v50, v110
	v_mul_f32_e32 v51, v51, v111
	v_mul_f32_e32 v52, v52, v112
	v_mul_f32_e32 v53, v53, v113
	v_mul_f32_e32 v54, v54, v250
	v_mul_f32_e32 v55, v55, v251
	v_mov_b32_e32 v108, s30
	v_mov_b32_e32 v109, s31
	v_mov_b32_e32 v110, s34
	v_mov_b32_e32 v111, s35
	v_mov_b32_e32 v112, s36
	v_mov_b32_e32 v113, s37
	v_mov_b32_e32 v250, s38
	v_mov_b32_e32 v251, s39
	v_max_f32_e32 v108, 0x179abe15, v108
	v_max_f32_e32 v109, 0x179abe15, v109
	v_max_f32_e32 v110, 0x179abe15, v110
	v_max_f32_e32 v111, 0x179abe15, v111
	v_max_f32_e32 v112, 0x179abe15, v112
	v_max_f32_e32 v113, 0x179abe15, v113
	v_max_f32_e32 v250, 0x179abe15, v250
	v_max_f32_e32 v251, 0x179abe15, v251
	v_rsq_f32_e32 v108, v108
	v_rsq_f32_e32 v109, v109
	v_rsq_f32_e32 v110, v110
	v_rsq_f32_e32 v111, v111
	v_rsq_f32_e32 v112, v112
	v_rsq_f32_e32 v113, v113
	v_rsq_f32_e32 v250, v250
	v_rsq_f32_e32 v251, v251
	v_mul_f32_e32 v32, v32, v108
	v_mul_f32_e32 v33, v33, v109
	v_mul_f32_e32 v34, v34, v110
	v_mul_f32_e32 v35, v35, v111
	v_mul_f32_e32 v36, v36, v112
	v_mul_f32_e32 v37, v37, v113
	v_mul_f32_e32 v38, v38, v250
	v_mul_f32_e32 v39, v39, v251
	v_mul_f32_e32 v40, v40, v32
	v_mul_f32_e32 v41, v41, v33
	v_mul_f32_e32 v42, v42, v34
	v_mul_f32_e32 v43, v43, v35
	v_mul_f32_e32 v44, v44, v36
	v_mul_f32_e32 v45, v45, v37
	v_mul_f32_e32 v46, v46, v38
	v_mul_f32_e32 v47, v47, v39
	s_waitcnt lgkmcnt(5)
; __device__ __forceinline__ void chunkA_item(const Args& A, LAS unsigned char* lds, int tid, int lane, int wave, int ci, int ci_next, HeadConstA& H) {
;     ...
;             const float bc = wsum_fast(zr[i] * km * rkc); if (lane == 0) BCg[t] = bc;
	v_mul_f32_e32 v108, v64, v48
	v_mul_f32_e32 v109, v65, v49
	v_mul_f32_e32 v110, v66, v50
	v_mul_f32_e32 v111, v67, v51
	v_mul_f32_e32 v112, v68, v52
	v_mul_f32_e32 v113, v69, v53
	v_mul_f32_e32 v250, v70, v54
	v_mul_f32_e32 v251, v71, v55
	v_mul_f32_e32 v108, v213, v108
	v_mul_f32_e32 v109, v213, v109
	v_mul_f32_e32 v110, v213, v110
	v_mul_f32_e32 v111, v213, v111
	v_mul_f32_e32 v112, v213, v112
	v_mul_f32_e32 v113, v213, v113
	v_mul_f32_e32 v250, v213, v250
	v_mul_f32_e32 v251, v213, v251
	v_add_f32_dpp v108, v108, v108 quad_perm:[1,0,3,2] row_mask:0xf bank_mask:0xf
	v_add_f32_dpp v109, v109, v109 quad_perm:[1,0,3,2] row_mask:0xf bank_mask:0xf
	v_add_f32_dpp v110, v110, v110 quad_perm:[1,0,3,2] row_mask:0xf bank_mask:0xf
	v_add_f32_dpp v111, v111, v111 quad_perm:[1,0,3,2] row_mask:0xf bank_mask:0xf
	v_add_f32_dpp v112, v112, v112 quad_perm:[1,0,3,2] row_mask:0xf bank_mask:0xf
	v_add_f32_dpp v113, v113, v113 quad_perm:[1,0,3,2] row_mask:0xf bank_mask:0xf
	v_add_f32_dpp v250, v250, v250 quad_perm:[1,0,3,2] row_mask:0xf bank_mask:0xf
	v_add_f32_dpp v251, v251, v251 quad_perm:[1,0,3,2] row_mask:0xf bank_mask:0xf
	v_add_f32_dpp v108, v108, v108 quad_perm:[2,3,0,1] row_mask:0xf bank_mask:0xf
	v_add_f32_dpp v109, v109, v109 quad_perm:[2,3,0,1] row_mask:0xf bank_mask:0xf
	v_add_f32_dpp v110, v110, v110 quad_perm:[2,3,0,1] row_mask:0xf bank_mask:0xf
	v_add_f32_dpp v111, v111, v111 quad_perm:[2,3,0,1] row_mask:0xf bank_mask:0xf
	v_add_f32_dpp v112, v112, v112 quad_perm:[2,3,0,1] row_mask:0xf bank_mask:0xf
	v_add_f32_dpp v113, v113, v113 quad_perm:[2,3,0,1] row_mask:0xf bank_mask:0xf
	v_add_f32_dpp v250, v250, v250 quad_perm:[2,3,0,1] row_mask:0xf bank_mask:0xf
	v_add_f32_dpp v251, v251, v251 quad_perm:[2,3,0,1] row_mask:0xf bank_mask:0xf
	v_add_f32_dpp v108, v108, v108 row_half_mirror row_mask:0xf bank_mask:0xf
	v_add_f32_dpp v109, v109, v109 row_half_mirror row_mask:0xf bank_mask:0xf
	v_add_f32_dpp v110, v110, v110 row_half_mirror row_mask:0xf bank_mask:0xf
	v_add_f32_dpp v111, v111, v111 row_half_mirror row_mask:0xf bank_mask:0xf
	v_add_f32_dpp v112, v112, v112 row_half_mirror row_mask:0xf bank_mask:0xf
	v_add_f32_dpp v113, v113, v113 row_half_mirror row_mask:0xf bank_mask:0xf
	v_add_f32_dpp v250, v250, v250 row_half_mirror row_mask:0xf bank_mask:0xf
	v_add_f32_dpp v251, v251, v251 row_half_mirror row_mask:0xf bank_mask:0xf
	v_add_f32_dpp v108, v108, v108 row_mirror row_mask:0xf bank_mask:0xf
	v_add_f32_dpp v109, v109, v109 row_mirror row_mask:0xf bank_mask:0xf
	v_add_f32_dpp v110, v110, v110 row_mirror row_mask:0xf bank_mask:0xf
	v_add_f32_dpp v111, v111, v111 row_mirror row_mask:0xf bank_mask:0xf
	v_add_f32_dpp v112, v112, v112 row_mirror row_mask:0xf bank_mask:0xf
	v_add_f32_dpp v113, v113, v113 row_mirror row_mask:0xf bank_mask:0xf
	v_add_f32_dpp v250, v250, v250 row_mirror row_mask:0xf bank_mask:0xf
	v_add_f32_dpp v251, v251, v251 row_mirror row_mask:0xf bank_mask:0xf
	v_add_f32_dpp v108, v108, v108 row_bcast:15 row_mask:0xa bank_mask:0xf
	v_add_f32_dpp v109, v109, v109 row_bcast:15 row_mask:0xa bank_mask:0xf
	v_add_f32_dpp v110, v110, v110 row_bcast:15 row_mask:0xa bank_mask:0xf
	v_add_f32_dpp v111, v111, v111 row_bcast:15 row_mask:0xa bank_mask:0xf
	v_add_f32_dpp v112, v112, v112 row_bcast:15 row_mask:0xa bank_mask:0xf
	v_add_f32_dpp v113, v113, v113 row_bcast:15 row_mask:0xa bank_mask:0xf
	v_add_f32_dpp v250, v250, v250 row_bcast:15 row_mask:0xa bank_mask:0xf
	v_add_f32_dpp v251, v251, v251 row_bcast:15 row_mask:0xa bank_mask:0xf
	v_add_f32_dpp v108, v108, v108 row_bcast:31 row_mask:0xc bank_mask:0xf
	v_add_f32_dpp v109, v109, v109 row_bcast:31 row_mask:0xc bank_mask:0xf
	v_add_f32_dpp v110, v110, v110 row_bcast:31 row_mask:0xc bank_mask:0xf
	v_add_f32_dpp v111, v111, v111 row_bcast:31 row_mask:0xc bank_mask:0xf
	v_add_f32_dpp v112, v112, v112 row_bcast:31 row_mask:0xc bank_mask:0xf
	v_add_f32_dpp v113, v113, v113 row_bcast:31 row_mask:0xc bank_mask:0xf
	v_add_f32_dpp v250, v250, v250 row_bcast:31 row_mask:0xc bank_mask:0xf
	v_add_f32_dpp v251, v251, v251 row_bcast:31 row_mask:0xc bank_mask:0xf
	s_mov_b64 exec, s[100:101]
	global_store_dword v105, v108, s[78:79]
	global_store_dword v105, v109, s[78:79] offset:4
	global_store_dword v105, v110, s[78:79] offset:8
	global_store_dword v105, v111, s[78:79] offset:12
	global_store_dword v105, v112, s[78:79] offset:16
	global_store_dword v105, v113, s[78:79] offset:20
	global_store_dword v105, v250, s[78:79] offset:24
	global_store_dword v105, v251, s[78:79] offset:28
	s_mov_b64 exec, -1
	s_waitcnt lgkmcnt(0)
	s_barrier
; #define LAS __attribute__((address_space(3)))
; __device__ __forceinline__ unsigned f2bf(float f) { return pk2(f, 0.f) & 0xffffu; }
; __device__ __forceinline__ void chunkA_item(const Args& A, LAS unsigned char* lds, int tid, int lane, int wave, int ci, int ci_next, HeadConstA& H) {
;     ...
;         float off = 0.f, tot = 0.f;
; #pragma unroll
;         for (int s = 0; s < 8; ++s) { const float v = ((LAS float*)(lds + CA_SEG))[s * 64 + cc]; tot += v; if (s < seg) off += v; }
;         const float kkc = H.kkc, kac = H.kac, rkc = H.rkc;
;         float rhs8[8], nbh8[8], kh8[8];
;         float* BCg = (float*)(A.ws + WS_BC) + (size_t)ci * 64;
; #pragma unroll
;         for (int i = 0; i < 8; ++i) { const int t = seg * 8 + i;
;             const float lg = off + pre[i], lgp = lg - lwv[i];
;             const float kkraw = zk[i] * kkc; const float n2 = wsum_fast(kkraw * kkraw); const float kk = kkraw * __builtin_amdgcn_rsqf(fmaxf(n2, 1e-24f));
;             const float a = av[i], bb = kk * a, km = zk[i] * (1.f + (a - 1.f) * kac);
;             const float bc = wsum_fast(zr[i] * km * rkc); if (lane == 0) BCg[t] = bc;
;             const float e_in = __expf(lg), e_pr = __expf(lgp), e_out = __expf(-lg), e_h = __expf(tot - lg);
;             const float kkt = kk * e_pr; rhs8[i] = kkt; nbh8[i] = -(bb * e_h); kh8[i] = km * e_h;
;             *(LAS unsigned short*)(lds + CA_KKT + t * 144 + cc * 2) = (unsigned short)f2bf(kkt);
;             *(LAS unsigned short*)(lds + CA_RT + t * 144 + cc * 2) = (unsigned short)f2bf(zr[i] * e_in);
;             *(LAS unsigned short*)(lds + CA_BT + t * 144 + cc * 2) = (unsigned short)f2bf(bb * e_out);
;             *(LAS unsigned short*)(lds + CA_KT + t * 144 + cc * 2) = (unsigned short)f2bf(km * e_out); }
	ds_read2st64_b32 v[108:109], v79 offset0:0 offset1:1
	ds_read2st64_b32 v[110:111], v79 offset0:2 offset1:3
	ds_read2st64_b32 v[112:113], v79 offset0:4 offset1:5
	ds_read2st64_b32 v[250:251], v79 offset0:6 offset1:7
	s_waitcnt lgkmcnt(0)
	v_mov_b32_e32 v72, 0
	v_mov_b32_e32 v222, v108
	s_cmp_gt_u32 s24, 0
	s_cselect_b32 s40, 1.0, 0
	v_fmac_f32_e32 v72, s40, v108
	v_add_f32_e32 v222, v222, v109
	s_cmp_gt_u32 s24, 1
	s_cselect_b32 s40, 1.0, 0
	v_fmac_f32_e32 v72, s40, v109
	v_add_f32_e32 v222, v222, v110
	s_cmp_gt_u32 s24, 2
	s_cselect_b32 s40, 1.0, 0
	v_fmac_f32_e32 v72, s40, v110
	v_add_f32_e32 v222, v222, v111
	s_cmp_gt_u32 s24, 3
	s_cselect_b32 s40, 1.0, 0
	v_fmac_f32_e32 v72, s40, v111
	v_add_f32_e32 v222, v222, v112
	s_cmp_gt_u32 s24, 4
	s_cselect_b32 s40, 1.0, 0
	v_fmac_f32_e32 v72, s40, v112
	v_add_f32_e32 v222, v222, v113
	s_cmp_gt_u32 s24, 5
	s_cselect_b32 s40, 1.0, 0
	v_fmac_f32_e32 v72, s40, v113
	v_add_f32_e32 v222, v222, v250
	s_cmp_gt_u32 s24, 6
	s_cselect_b32 s40, 1.0, 0
	v_fmac_f32_e32 v72, s40, v250
	v_add_f32_e32 v222, v222, v251
	v_add_f32_e32 v214, v72, v214
	v_add_f32_e32 v215, v72, v215
	v_add_f32_e32 v216, v72, v216
	v_add_f32_e32 v217, v72, v217
	v_add_f32_e32 v218, v72, v218
	v_add_f32_e32 v219, v72, v219
	v_add_f32_e32 v220, v72, v220
	v_add_f32_e32 v221, v72, v221
	v_sub_f32_e32 v226, v214, v226
	v_sub_f32_e32 v227, v215, v227
	v_sub_f32_e32 v228, v216, v228
	v_sub_f32_e32 v229, v217, v229
	v_sub_f32_e32 v230, v218, v230
	v_sub_f32_e32 v231, v219, v231
	v_sub_f32_e32 v232, v220, v232
	v_sub_f32_e32 v233, v221, v233
	v_mul_f32_e32 v226, 0x3fb8aa3b, v226
	v_mul_f32_e32 v227, 0x3fb8aa3b, v227
	v_mul_f32_e32 v228, 0x3fb8aa3b, v228
	v_mul_f32_e32 v229, 0x3fb8aa3b, v229
	v_mul_f32_e32 v230, 0x3fb8aa3b, v230
	v_mul_f32_e32 v231, 0x3fb8aa3b, v231
	v_mul_f32_e32 v232, 0x3fb8aa3b, v232
	v_mul_f32_e32 v233, 0x3fb8aa3b, v233
	v_exp_f32_e32 v226, v226
	v_exp_f32_e32 v227, v227
	v_exp_f32_e32 v228, v228
	v_exp_f32_e32 v229, v229
	v_exp_f32_e32 v230, v230
	v_exp_f32_e32 v231, v231
	v_exp_f32_e32 v232, v232
	v_exp_f32_e32 v233, v233
	v_mul_f32_e32 v32, v226, v32
	v_mul_f32_e32 v33, v227, v33
	v_mul_f32_e32 v34, v228, v34
	v_mul_f32_e32 v35, v229, v35
	v_mul_f32_e32 v36, v230, v36
	v_mul_f32_e32 v37, v231, v37
	v_mul_f32_e32 v38, v232, v38
	v_mul_f32_e32 v39, v233, v39
	v_cvt_pk_bf16_f32 v108, v32, v32
	v_cvt_pk_bf16_f32 v109, v33, v33
	v_cvt_pk_bf16_f32 v110, v34, v34
	v_cvt_pk_bf16_f32 v111, v35, v35
	v_cvt_pk_bf16_f32 v112, v36, v36
	v_cvt_pk_bf16_f32 v113, v37, v37
	v_cvt_pk_bf16_f32 v250, v38, v38
	v_cvt_pk_bf16_f32 v251, v39, v39
	ds_write_b16 v103, v108 offset:0
	ds_write_b16 v103, v109 offset:144
	ds_write_b16 v103, v110 offset:288
	ds_write_b16 v103, v111 offset:432
	ds_write_b16 v103, v112 offset:576
	ds_write_b16 v103, v113 offset:720
	ds_write_b16 v103, v250 offset:864
	ds_write_b16 v103, v251 offset:1008
	v_mul_f32_e32 v226, 0x3fb8aa3b, v214
	v_mul_f32_e32 v227, 0x3fb8aa3b, v215
	v_mul_f32_e32 v228, 0x3fb8aa3b, v216
	v_mul_f32_e32 v229, 0x3fb8aa3b, v217
	v_mul_f32_e32 v230, 0x3fb8aa3b, v218
	v_mul_f32_e32 v231, 0x3fb8aa3b, v219
	v_mul_f32_e32 v232, 0x3fb8aa3b, v220
	v_mul_f32_e32 v233, 0x3fb8aa3b, v221
	v_exp_f32_e32 v226, v226
	v_exp_f32_e32 v227, v227
	v_exp_f32_e32 v228, v228
	v_exp_f32_e32 v229, v229
	v_exp_f32_e32 v230, v230
	v_exp_f32_e32 v231, v231
	v_exp_f32_e32 v232, v232
	v_exp_f32_e32 v233, v233
	v_mul_f32_e32 v64, v64, v226
	v_mul_f32_e32 v65, v65, v227
	v_mul_f32_e32 v66, v66, v228
	v_mul_f32_e32 v67, v67, v229
	v_mul_f32_e32 v68, v68, v230
	v_mul_f32_e32 v69, v69, v231
	v_mul_f32_e32 v70, v70, v232
	v_mul_f32_e32 v71, v71, v233
	v_cvt_pk_bf16_f32 v108, v64, v64
	v_cvt_pk_bf16_f32 v109, v65, v65
	v_cvt_pk_bf16_f32 v110, v66, v66
	v_cvt_pk_bf16_f32 v111, v67, v67
	v_cvt_pk_bf16_f32 v112, v68, v68
	v_cvt_pk_bf16_f32 v113, v69, v69
	v_cvt_pk_bf16_f32 v250, v70, v70
	v_cvt_pk_bf16_f32 v251, v71, v71
	ds_write_b16 v103, v108 offset:27648
	ds_write_b16 v103, v109 offset:27792
	ds_write_b16 v103, v110 offset:27936
	ds_write_b16 v103, v111 offset:28080
	ds_write_b16 v103, v112 offset:28224
	ds_write_b16 v103, v113 offset:28368
	ds_write_b16 v103, v250 offset:28512
; #define LAS __attribute__((address_space(3)))
; __device__ __forceinline__ unsigned f2bf(float f) { return pk2(f, 0.f) & 0xffffu; }
; __device__ __forceinline__ u32x4 pack8(const float* f) { u32x4 o; o.x = pk2(f[0], f[1]); o.y = pk2(f[2], f[3]); o.z = pk2(f[4], f[5]); o.w = pk2(f[6], f[7]); return o; }
; __device__ __forceinline__ void chunkA_item(const Args& A, LAS unsigned char* lds, int tid, int lane, int wave, int ci, int ci_next, HeadConstA& H) {
;     ...
;             const float e_in = __expf(lg), e_pr = __expf(lgp), e_out = __expf(-lg), e_h = __expf(tot - lg);
;             const float kkt = kk * e_pr; rhs8[i] = kkt; nbh8[i] = -(bb * e_h); kh8[i] = km * e_h;
;             *(LAS unsigned short*)(lds + CA_KKT + t * 144 + cc * 2) = (unsigned short)f2bf(kkt);
;             *(LAS unsigned short*)(lds + CA_RT + t * 144 + cc * 2) = (unsigned short)f2bf(zr[i] * e_in);
;             *(LAS unsigned short*)(lds + CA_BT + t * 144 + cc * 2) = (unsigned short)f2bf(bb * e_out);
;             *(LAS unsigned short*)(lds + CA_KT + t * 144 + cc * 2) = (unsigned short)f2bf(km * e_out); }
;         *(LAS u32x4*)(lds + CA_NBHT + cc * 144 + seg * 16) = pack8(nbh8); *(LAS u32x4*)(lds + CA_KHT + cc * 144 + seg * 16) = pack8(kh8); *(LAS u32x4*)(lds + CA_VT + cc * 144 + seg * 16) = pack8(zv);
;         LAS f32x4* rp = (LAS f32x4*)(lds + CA_RHS + (cc * 68 + seg * 8) * 4); rp[0] = (f32x4){rhs8[0], rhs8[1], rhs8[2], rhs8[3]}; rp[1] = (f32x4){rhs8[4], rhs8[5], rhs8[6], rhs8[7]};
;         if (seg == 0) ((LAS float*)(lds + CA_G))[cc] = __expf(tot);
	ds_write_b16 v103, v251 offset:28656
	v_mul_f32_e32 v226, 0xbfb8aa3b, v214
	v_mul_f32_e32 v227, 0xbfb8aa3b, v215
	v_mul_f32_e32 v228, 0xbfb8aa3b, v216
	v_mul_f32_e32 v229, 0xbfb8aa3b, v217
	v_mul_f32_e32 v230, 0xbfb8aa3b, v218
	v_mul_f32_e32 v231, 0xbfb8aa3b, v219
	v_mul_f32_e32 v232, 0xbfb8aa3b, v220
	v_mul_f32_e32 v233, 0xbfb8aa3b, v221
	v_exp_f32_e32 v226, v226
	v_exp_f32_e32 v227, v227
	v_exp_f32_e32 v228, v228
	v_exp_f32_e32 v229, v229
	v_exp_f32_e32 v230, v230
	v_exp_f32_e32 v231, v231
	v_exp_f32_e32 v232, v232
	v_exp_f32_e32 v233, v233
	v_mul_f32_e32 v64, v226, v40
	v_mul_f32_e32 v65, v227, v41
	v_mul_f32_e32 v66, v228, v42
	v_mul_f32_e32 v67, v229, v43
	v_mul_f32_e32 v68, v230, v44
	v_mul_f32_e32 v69, v231, v45
	v_mul_f32_e32 v70, v232, v46
	v_mul_f32_e32 v71, v233, v47
	v_cvt_pk_bf16_f32 v108, v64, v64
	v_cvt_pk_bf16_f32 v109, v65, v65
	v_cvt_pk_bf16_f32 v110, v66, v66
	v_cvt_pk_bf16_f32 v111, v67, v67
	v_cvt_pk_bf16_f32 v112, v68, v68
	v_cvt_pk_bf16_f32 v113, v69, v69
	v_cvt_pk_bf16_f32 v250, v70, v70
	v_cvt_pk_bf16_f32 v251, v71, v71
	ds_write_b16 v103, v108 offset:9216
	ds_write_b16 v103, v109 offset:9360
	ds_write_b16 v103, v110 offset:9504
	ds_write_b16 v103, v111 offset:9648
	ds_write_b16 v103, v112 offset:9792
	ds_write_b16 v103, v113 offset:9936
	ds_write_b16 v103, v250 offset:10080
	ds_write_b16 v103, v251 offset:10224
	v_mul_f32_e32 v64, v48, v226
	v_mul_f32_e32 v65, v49, v227
	v_mul_f32_e32 v66, v50, v228
	v_mul_f32_e32 v67, v51, v229
	v_mul_f32_e32 v68, v52, v230
	v_mul_f32_e32 v69, v53, v231
	v_mul_f32_e32 v70, v54, v232
	v_mul_f32_e32 v71, v55, v233
	v_cvt_pk_bf16_f32 v108, v64, v64
	v_cvt_pk_bf16_f32 v109, v65, v65
	v_cvt_pk_bf16_f32 v110, v66, v66
	v_cvt_pk_bf16_f32 v111, v67, v67
	v_cvt_pk_bf16_f32 v112, v68, v68
	v_cvt_pk_bf16_f32 v113, v69, v69
	v_cvt_pk_bf16_f32 v250, v70, v70
	v_cvt_pk_bf16_f32 v251, v71, v71
	ds_write_b16 v103, v108 offset:18432
	ds_write_b16 v103, v109 offset:18576
	ds_write_b16 v103, v110 offset:18720
	ds_write_b16 v103, v111 offset:18864
	ds_write_b16 v103, v112 offset:19008
	ds_write_b16 v103, v113 offset:19152
	ds_write_b16 v103, v250 offset:19296
	ds_write_b16 v103, v251 offset:19440
	v_sub_f32_e32 v226, v222, v214
	v_sub_f32_e32 v227, v222, v215
	v_sub_f32_e32 v228, v222, v216
	v_sub_f32_e32 v229, v222, v217
	v_sub_f32_e32 v230, v222, v218
	v_sub_f32_e32 v231, v222, v219
	v_sub_f32_e32 v232, v222, v220
	v_sub_f32_e32 v233, v222, v221
	v_mul_f32_e32 v226, 0x3fb8aa3b, v226
	v_mul_f32_e32 v227, 0x3fb8aa3b, v227
	v_mul_f32_e32 v228, 0x3fb8aa3b, v228
	v_mul_f32_e32 v229, 0x3fb8aa3b, v229
	v_mul_f32_e32 v230, 0x3fb8aa3b, v230
	v_mul_f32_e32 v231, 0x3fb8aa3b, v231
	v_mul_f32_e32 v232, 0x3fb8aa3b, v232
	v_mul_f32_e32 v233, 0x3fb8aa3b, v233
	v_exp_f32_e32 v226, v226
	v_exp_f32_e32 v227, v227
	v_exp_f32_e32 v228, v228
	v_exp_f32_e32 v229, v229
	v_exp_f32_e32 v230, v230
	v_exp_f32_e32 v231, v231
	v_exp_f32_e32 v232, v232
	v_exp_f32_e32 v233, v233
	v_mul_f32_e64 v40, v40, -v226
	v_mul_f32_e64 v41, v41, -v227
	v_mul_f32_e64 v42, v42, -v228
	v_mul_f32_e64 v43, v43, -v229
	v_mul_f32_e64 v44, v44, -v230
	v_mul_f32_e64 v45, v45, -v231
	v_mul_f32_e64 v46, v46, -v232
	v_mul_f32_e64 v47, v47, -v233
	v_mul_f32_e32 v48, v48, v226
	v_mul_f32_e32 v49, v49, v227
	v_mul_f32_e32 v50, v50, v228
	v_mul_f32_e32 v51, v51, v229
	v_mul_f32_e32 v52, v52, v230
	v_mul_f32_e32 v53, v53, v231
	v_mul_f32_e32 v54, v54, v232
	v_mul_f32_e32 v55, v55, v233
	v_cvt_pk_bf16_f32 v40, v40, v41
	v_cvt_pk_bf16_f32 v41, v42, v43
	v_cvt_pk_bf16_f32 v42, v44, v45
	v_cvt_pk_bf16_f32 v43, v46, v47
	v_cvt_pk_bf16_f32 v48, v48, v49
	v_cvt_pk_bf16_f32 v49, v50, v51
	v_cvt_pk_bf16_f32 v50, v52, v53
	v_cvt_pk_bf16_f32 v51, v54, v55
	v_cvt_pk_bf16_f32 v56, v56, v57
	v_cvt_pk_bf16_f32 v57, v58, v59
	v_cvt_pk_bf16_f32 v58, v60, v61
	v_cvt_pk_bf16_f32 v59, v62, v63
	ds_write_b128 v181, v[40:43] offset:36864
	ds_write_b128 v181, v[48:51] offset:46080
	ds_write_b128 v181, v[56:59] offset:55296
	ds_write_b128 v182, v[32:35] offset:64512
	ds_write_b128 v182, v[36:39] offset:64528
	s_andn2_b64 vcc, exec, s[14:15]
	s_cbranch_vccnz .La3_skip_g
	v_mul_f32_e32 v108, 0x3fb8aa3b, v222
	v_exp_f32_e32 v108, v108
	ds_write_b32 v165, v108

; __device__ __forceinline__ void chunkA_item(const Args& A, LAS unsigned char* lds, int tid, int lane, int wave, int ci, int ci_next, HeadConstA& H) {
;     ...
;         for (int nn = 0; nn < 2; ++nn) { const int nt = (wave & 1) * 2 + nn; f32x4 acc = {0.f, 0.f, 0.f, 0.f};
; #pragma unroll
;             for (int ks = 0; ks < 2; ++ks) acc = MFMA16(aM[ks], ldsfrag(lds + CA_VT, nt * 16 + fr, ks * 32 + q4 * 8), acc);
;             *(LAS f32x4*)(lds + CA_RHS + ((64 + nt * 16 + fr) * 68 + mt * 16 + q4 * 4) * 4) = acc; }
;     }
;     LBAR();
;     if (tid < 256) {
;         const int cp = tid >> 2, q = tid & 3;
;         f32x2_t xa[8], xb[8];
; #pragma unroll
;         for (int m = 0; m < 8; ++m) { xa[m] = (f32x2_t){0.f, 0.f}; xb[m] = (f32x2_t){0.f, 0.f}; }
;         const LAS float* Np = (const LAS float*)(lds + CA_N) + q * 16;
;         const LAS float* Ra = (const LAS float*)(lds + CA_RHS) + cp * 68; const LAS float* Rb = Ra + 64 * 68;
;         float a4[4], b4[4];
; #pragma unroll
;         for (int t = 0; t < 64; ++t) {
;             f32x2_t sa = {0.f, 0.f}, sb = {0.f, 0.f};
; #pragma unroll
;             for (int p = 0; p < ((t + 3) / 4 + 1) / 2; ++p) { const f32x2_t nv = *(const LAS f32x2_t*)(Np + t * 64 + 2 * p); sa += nv * xa[p]; sb += nv * xb[p]; }
;             float ua = sa.x + sa.y, ub = sb.x + sb.y;
;             ua += dppf<0xB1>(ua); ub += dppf<0xB1>(ub); ua += dppf<0x4E>(ua); ub += dppf<0x4E>(ub);
;             const float xta = Ra[t] - ua, xtb = Rb[t] - ub;
;             if (q == (t & 3)) { if ((t >> 2) & 1) { xa[t >> 3].y = xta; xb[t >> 3].y = xtb; } else { xa[t >> 3].x = xta; xb[t >> 3].x = xtb; } }
;             a4[t & 3] = xta; b4[t & 3] = xtb;
;             if ((t & 3) == 3 && q == 0) { *(LAS u32x2*)(lds + CA_XT + cp * 144 + (t - 3) * 2) = pack4(a4[0], a4[1], a4[2], a4[3]);
;                 *(LAS u32x2*)(lds + CA_XT + (64 + cp) * 144 + (t - 3) * 2) = pack4(b4[0], b4[1], b4[2], b4[3]); }
;         }
;     } else if (ci_next < 4096) {
;         const int cn = ci_next & 31, hn = (ci_next >> 5) & 7, bn = ci_next >> 8; const long rown = (long)bn * SEQ + cn * 64 - 1;
;         for (int l = tid - 256; l < 65 * 5; l += 256) { const int r = l / 5, sec = l % 5; long rr = rown + r; if (rr < 0) rr = 0;
;             const bf16_t* p = Z + rr * NZ + (sec == 0 ? hn * 64 : sec == 1 ? 512 + hn * 64 : sec == 2 ? 1024 + hn * 64 : sec == 3 ? 1536 : 1600);
.LBB0_210:
	s_waitcnt lgkmcnt(0)
	s_barrier
	v_add_u32_e32 v48, v171, v172
	ds_read_b128 v[32:35], v187
	ds_read_b128 v[36:39], v187 offset:64
	ds_read_b128 v[40:43], v48 offset:55296
	ds_read_b128 v[44:47], v48 offset:55360
	s_add_i32 s42, s28, s33
	s_waitcnt lgkmcnt(1)
	v_mfma_f32_16x16x32_bf16 v[40:43], v[32:35], v[40:43], 0
	s_waitcnt lgkmcnt(0)
	v_mfma_f32_16x16x32_bf16 v[40:43], v[36:39], v[44:47], v[40:43]
	s_nop 7
	ds_write_b128 v173, v[40:43] offset:17408
	ds_read_b128 v[40:43], v48 offset:57600
	ds_read_b128 v[44:47], v48 offset:57664
	s_waitcnt lgkmcnt(1)
	v_mfma_f32_16x16x32_bf16 v[32:35], v[32:35], v[40:43], 0
	s_waitcnt lgkmcnt(0)
	v_mfma_f32_16x16x32_bf16 v[32:35], v[36:39], v[44:47], v[32:35]
	s_nop 7
	ds_write_b128 v174, v[32:35] offset:17408
	s_waitcnt lgkmcnt(0)
	s_barrier
	s_cmpk_gt_i32 s42, 0xfff
	s_cbranch_scc1 .La6_nopf
	s_and_b32 s24, s42, 31
	s_lshl_b32 s24, s24, 6
	s_ashr_i32 s25, s42, 8
	s_lshl_b32 s25, s25, 11
	s_add_i32 s24, s24, s25
	s_add_i32 s24, s24, -1
	s_mul_i32 s24, s24, 0x1c00
	s_add_u32 s30, s94, s24
	s_addc_u32 s31, s95, 0
	s_bfe_u32 s25, s42, 0x30005
	v_mad_u32_u24 v72, v185, s25, v184
	v_cmp_gt_u32_e32 vcc, 0x145, v144
	s_and_saveexec_b64 s[24:25], vcc
	global_load_dword v186, v72, s[30:31]
	s_or_b64 exec, exec, s[24:25]
.La6_nopf:
	v_and_b32_e32 v72, 3, v144
	v_lshl_add_u32 v72, v72, 2, v177
	ds_read_b32 v32, v72 offset:64512
	ds_read_b32 v33, v72 offset:64528
	ds_read_b32 v34, v72 offset:64544
	ds_read_b32 v35, v72 offset:64560
	ds_read_b32 v36, v72 offset:64576
	ds_read_b32 v37, v72 offset:64592
	ds_read_b32 v38, v72 offset:64608
	ds_read_b32 v39, v72 offset:64624
	ds_read_b32 v40, v72 offset:64640
	ds_read_b32 v41, v72 offset:64656
	ds_read_b32 v42, v72 offset:64672
	ds_read_b32 v43, v72 offset:64688
	ds_read_b32 v44, v72 offset:64704
	ds_read_b32 v45, v72 offset:64720
	ds_read_b32 v46, v72 offset:64736
	ds_read_b32 v47, v72 offset:64752
	ds_read_b128 v[64:67], v176 offset:0
	ds_read_b128 v[68:71], v176 offset:16
	ds_read_b128 v[108:111], v176 offset:32
	ds_read_b128 v[214:217], v176 offset:48
	ds_read_b128 v[218:221], v176 offset:256
	ds_read_b128 v[226:229], v176 offset:272
	ds_read_b128 v[230:233], v176 offset:288
	ds_read_b128 v[48:51], v176 offset:304
	ds_read_b128 v[52:55], v176 offset:512
	ds_read_b128 v[56:59], v176 offset:528
	s_waitcnt lgkmcnt(10)
	v_mov_b32_dpp v250, v32 quad_perm:[0,0,0,0] row_mask:0xf bank_mask:0xf
	s_waitcnt lgkmcnt(9)
	v_fma_f32 v32, -v64, v250, v32
	v_fma_f32 v33, -v65, v250, v33
	v_fma_f32 v34, -v66, v250, v34
	v_fma_f32 v35, -v67, v250, v35
	ds_read_b128 v[60:63], v176 offset:544
	s_waitcnt lgkmcnt(9)
	v_fma_f32 v36, -v68, v250, v36
	v_fma_f32 v37, -v69, v250, v37
	v_fma_f32 v38, -v70, v250, v38
	v_fma_f32 v39, -v71, v250, v39
	ds_read_b128 v[64:67], v176 offset:560
	s_waitcnt lgkmcnt(9)
	v_fma_f32 v40, -v108, v250, v40
	v_fma_f32 v41, -v109, v250, v41
	v_fma_f32 v42, -v110, v250, v42
	v_fma_f32 v43, -v111, v250, v43
	ds_read_b128 v[68:71], v176 offset:768
	s_waitcnt lgkmcnt(9)
	v_fma_f32 v44, -v214, v250, v44
	v_fma_f32 v45, -v215, v250, v45
	v_fma_f32 v46, -v216, v250, v46
	v_fma_f32 v47, -v217, v250, v47
	ds_read_b128 v[108:111], v176 offset:784
	v_mov_b32_dpp v254, v32 quad_perm:[1,1,1,1] row_mask:0xf bank_mask:0xf
	s_waitcnt lgkmcnt(9)
	v_fma_f32 v32, -v218, v254, v32
	v_fma_f32 v33, -v219, v254, v33
	v_fma_f32 v34, -v220, v254, v34
	v_fma_f32 v35, -v221, v254, v35
	ds_read_b128 v[214:217], v176 offset:800
	s_waitcnt lgkmcnt(9)
	v_fma_f32 v36, -v226, v254, v36
	v_fma_f32 v37, -v227, v254, v37
	v_fma_f32 v38, -v228, v254, v38
	v_fma_f32 v39, -v229, v254, v39
	ds_read_b128 v[218:221], v176 offset:816
	s_waitcnt lgkmcnt(9)
	v_fma_f32 v40, -v230, v254, v40
	v_fma_f32 v41, -v231, v254, v41
	v_fma_f32 v42, -v232, v254, v42
	v_fma_f32 v43, -v233, v254, v43
	ds_read_b128 v[226:229], v176 offset:1024
	s_waitcnt lgkmcnt(9)
	v_fma_f32 v44, -v48, v254, v44
	v_fma_f32 v45, -v49, v254, v45
	v_fma_f32 v46, -v50, v254, v46
	v_fma_f32 v47, -v51, v254, v47
	ds_read_b128 v[230:233], v176 offset:1040
	v_cvt_pk_bf16_f32 v252, v250, v254
	v_mov_b32_dpp v250, v32 quad_perm:[2,2,2,2] row_mask:0xf bank_mask:0xf
	s_waitcnt lgkmcnt(9)
	v_fma_f32 v32, -v52, v250, v32
	v_fma_f32 v33, -v53, v250, v33
	v_fma_f32 v34, -v54, v250, v34
	v_fma_f32 v35, -v55, v250, v35
	ds_read_b128 v[48:51], v176 offset:1056
	s_waitcnt lgkmcnt(9)
	v_fma_f32 v36, -v56, v250, v36
	v_fma_f32 v37, -v57, v250, v37
	v_fma_f32 v38, -v58, v250, v38
	v_fma_f32 v39, -v59, v250, v39
	ds_read_b128 v[52:55], v176 offset:1072
	s_waitcnt lgkmcnt(9)
	v_fma_f32 v40, -v60, v250, v40
	v_fma_f32 v41, -v61, v250, v41
	v_fma_f32 v42, -v62, v250, v42
	v_fma_f32 v43, -v63, v250, v43
	ds_read_b128 v[56:59], v176 offset:1280
	s_waitcnt lgkmcnt(9)
	v_fma_f32 v44, -v64, v250, v44
	v_fma_f32 v45, -v65, v250, v45
	v_fma_f32 v46, -v66, v250, v46
	v_fma_f32 v47, -v67, v250, v47
	ds_read_b128 v[60:63], v176 offset:1296
	v_mov_b32_dpp v254, v32 quad_perm:[3,3,3,3] row_mask:0xf bank_mask:0xf
	s_waitcnt lgkmcnt(9)
	v_fma_f32 v32, -v68, v254, v32
	v_fma_f32 v33, -v69, v254, v33
	v_fma_f32 v34, -v70, v254, v34
	v_fma_f32 v35, -v71, v254, v35
	ds_read_b128 v[64:67], v176 offset:1312
	s_waitcnt lgkmcnt(9)
	v_fma_f32 v36, -v108, v254, v36
	v_fma_f32 v37, -v109, v254, v37
	v_fma_f32 v38, -v110, v254, v38
	v_fma_f32 v39, -v111, v254, v39
	ds_read_b128 v[68:71], v176 offset:1328
	s_waitcnt lgkmcnt(9)
	v_fma_f32 v40, -v214, v254, v40
	v_fma_f32 v41, -v215, v254, v41
	v_fma_f32 v42, -v216, v254, v42
	v_fma_f32 v43, -v217, v254, v43
	ds_read_b128 v[108:111], v176 offset:1536
	s_waitcnt lgkmcnt(9)
; #define LAS __attribute__((address_space(3)))
; template <int CTRL> __device__ __forceinline__ float dppf(float x) { return __builtin_bit_cast(float, __builtin_amdgcn_update_dpp(0, __builtin_bit_cast(int, x), CTRL, 0xf, 0xf, false)); }
; __device__ __forceinline__ u32x2 pack4(float a, float b, float c, float d) { u32x2 o; o.x = pk2(a, b); o.y = pk2(c, d); return o; }
; __device__ __forceinline__ void chunkA_item(const Args& A, LAS unsigned char* lds, int tid, int lane, int wave, int ci, int ci_next, HeadConstA& H) {
;     ...
;     if (tid < 256) {
;         const int cp = tid >> 2, q = tid & 3;
;         f32x2_t xa[8], xb[8];
; #pragma unroll
;         for (int m = 0; m < 8; ++m) { xa[m] = (f32x2_t){0.f, 0.f}; xb[m] = (f32x2_t){0.f, 0.f}; }
;         const LAS float* Np = (const LAS float*)(lds + CA_N) + q * 16;
;         const LAS float* Ra = (const LAS float*)(lds + CA_RHS) + cp * 68; const LAS float* Rb = Ra + 64 * 68;
;         float a4[4], b4[4];
; #pragma unroll
;         for (int t = 0; t < 64; ++t) {
;             f32x2_t sa = {0.f, 0.f}, sb = {0.f, 0.f};
; #pragma unroll
;             for (int p = 0; p < ((t + 3) / 4 + 1) / 2; ++p) { const f32x2_t nv = *(const LAS f32x2_t*)(Np + t * 64 + 2 * p); sa += nv * xa[p]; sb += nv * xb[p]; }
;             float ua = sa.x + sa.y, ub = sb.x + sb.y;
;             ua += dppf<0xB1>(ua); ub += dppf<0xB1>(ub); ua += dppf<0x4E>(ua); ub += dppf<0x4E>(ub);
;             const float xta = Ra[t] - ua, xtb = Rb[t] - ub;
;             if (q == (t & 3)) { if ((t >> 2) & 1) { xa[t >> 3].y = xta; xb[t >> 3].y = xtb; } else { xa[t >> 3].x = xta; xb[t >> 3].x = xtb; } }
;             a4[t & 3] = xta; b4[t & 3] = xtb;
;             if ((t & 3) == 3 && q == 0) { *(LAS u32x2*)(lds + CA_XT + cp * 144 + (t - 3) * 2) = pack4(a4[0], a4[1], a4[2], a4[3]);
;                 *(LAS u32x2*)(lds + CA_XT + (64 + cp) * 144 + (t - 3) * 2) = pack4(b4[0], b4[1], b4[2], b4[3]); }
;         }
	v_fma_f32 v44, -v218, v254, v44
	v_fma_f32 v45, -v219, v254, v45
	v_fma_f32 v46, -v220, v254, v46
	v_fma_f32 v47, -v221, v254, v47
	ds_read_b128 v[214:217], v176 offset:1552
	v_cvt_pk_bf16_f32 v253, v250, v254
	s_mov_b64 exec, s[54:55]
	ds_write_b64 v202, v[252:253] offset:0
	s_mov_b64 exec, -1
	v_mov_b32_dpp v250, v33 quad_perm:[0,0,0,0] row_mask:0xf bank_mask:0xf
	s_waitcnt lgkmcnt(10)
	v_fma_f32 v32, -v226, v250, v32
	v_fma_f32 v33, -v227, v250, v33
	v_fma_f32 v34, -v228, v250, v34
	v_fma_f32 v35, -v229, v250, v35
	ds_read_b128 v[218:221], v176 offset:1568
	s_waitcnt lgkmcnt(10)
	v_fma_f32 v36, -v230, v250, v36
	v_fma_f32 v37, -v231, v250, v37
	v_fma_f32 v38, -v232, v250, v38
	v_fma_f32 v39, -v233, v250, v39
	ds_read_b128 v[226:229], v176 offset:1584
	s_waitcnt lgkmcnt(10)
	v_fma_f32 v40, -v48, v250, v40
	v_fma_f32 v41, -v49, v250, v41
	v_fma_f32 v42, -v50, v250, v42
	v_fma_f32 v43, -v51, v250, v43
	ds_read_b128 v[230:233], v176 offset:1792
	s_waitcnt lgkmcnt(10)
	v_fma_f32 v44, -v52, v250, v44
	v_fma_f32 v45, -v53, v250, v45
	v_fma_f32 v46, -v54, v250, v46
	v_fma_f32 v47, -v55, v250, v47
	ds_read_b128 v[48:51], v176 offset:1808
	v_mov_b32_dpp v254, v33 quad_perm:[1,1,1,1] row_mask:0xf bank_mask:0xf
	s_waitcnt lgkmcnt(10)
	v_fma_f32 v32, -v56, v254, v32
	v_fma_f32 v33, -v57, v254, v33
	v_fma_f32 v34, -v58, v254, v34
	v_fma_f32 v35, -v59, v254, v35
	ds_read_b128 v[52:55], v176 offset:1824
	s_waitcnt lgkmcnt(10)
	v_fma_f32 v36, -v60, v254, v36
	v_fma_f32 v37, -v61, v254, v37
	v_fma_f32 v38, -v62, v254, v38
	v_fma_f32 v39, -v63, v254, v39
	ds_read_b128 v[56:59], v176 offset:1840
	s_waitcnt lgkmcnt(10)
	v_fma_f32 v40, -v64, v254, v40
	v_fma_f32 v41, -v65, v254, v41
	v_fma_f32 v42, -v66, v254, v42
	v_fma_f32 v43, -v67, v254, v43
	ds_read_b128 v[60:63], v176 offset:2048
	s_waitcnt lgkmcnt(10)
	v_fma_f32 v44, -v68, v254, v44
	v_fma_f32 v45, -v69, v254, v45
	v_fma_f32 v46, -v70, v254, v46
	v_fma_f32 v47, -v71, v254, v47
	ds_read_b128 v[64:67], v176 offset:2064
	v_cvt_pk_bf16_f32 v252, v250, v254
	v_mov_b32_dpp v250, v33 quad_perm:[2,2,2,2] row_mask:0xf bank_mask:0xf
	s_waitcnt lgkmcnt(10)
	v_fma_f32 v32, -v108, v250, v32
	v_fma_f32 v33, -v109, v250, v33
	v_fma_f32 v34, -v110, v250, v34
	v_fma_f32 v35, -v111, v250, v35
	ds_read_b128 v[68:71], v176 offset:2080
	s_waitcnt lgkmcnt(10)
	v_fma_f32 v36, -v214, v250, v36
	v_fma_f32 v37, -v215, v250, v37
	v_fma_f32 v38, -v216, v250, v38
	v_fma_f32 v39, -v217, v250, v39
	ds_read_b128 v[108:111], v176 offset:2096
	s_waitcnt lgkmcnt(9)
	v_fma_f32 v40, -v218, v250, v40
	v_fma_f32 v41, -v219, v250, v41
	v_fma_f32 v42, -v220, v250, v42
	v_fma_f32 v43, -v221, v250, v43
	ds_read_b128 v[214:217], v176 offset:2304
	s_waitcnt lgkmcnt(9)
	v_fma_f32 v44, -v226, v250, v44
	v_fma_f32 v45, -v227, v250, v45
	v_fma_f32 v46, -v228, v250, v46
	v_fma_f32 v47, -v229, v250, v47
	ds_read_b128 v[218:221], v176 offset:2320
	v_mov_b32_dpp v254, v33 quad_perm:[3,3,3,3] row_mask:0xf bank_mask:0xf
	s_waitcnt lgkmcnt(9)
	v_fma_f32 v34, -v232, v254, v34
	v_fma_f32 v35, -v233, v254, v35
	v_fma_f32 v32, -v230, v254, v32
	v_fma_f32 v33, -v231, v254, v33
	ds_read_b128 v[226:229], v176 offset:2336
	s_waitcnt lgkmcnt(9)
	v_fma_f32 v36, -v48, v254, v36
	v_fma_f32 v37, -v49, v254, v37
	v_fma_f32 v38, -v50, v254, v38
	v_fma_f32 v39, -v51, v254, v39
	ds_read_b128 v[230:233], v176 offset:2352
	s_waitcnt lgkmcnt(9)
	v_fma_f32 v40, -v52, v254, v40
	v_fma_f32 v41, -v53, v254, v41
	v_fma_f32 v42, -v54, v254, v42
	v_fma_f32 v43, -v55, v254, v43
	ds_read_b128 v[48:51], v176 offset:2560
	s_waitcnt lgkmcnt(9)
	v_fma_f32 v44, -v56, v254, v44
	v_fma_f32 v45, -v57, v254, v45
	v_fma_f32 v46, -v58, v254, v46
	v_fma_f32 v47, -v59, v254, v47
	ds_read_b128 v[52:55], v176 offset:2576
	v_cvt_pk_bf16_f32 v253, v250, v254
	s_mov_b64 exec, s[54:55]
	ds_write_b64 v202, v[252:253] offset:8
	s_mov_b64 exec, -1
	v_mov_b32_dpp v250, v34 quad_perm:[0,0,0,0] row_mask:0xf bank_mask:0xf
	s_waitcnt lgkmcnt(10)
	v_fma_f32 v34, -v62, v250, v34
	v_fma_f32 v35, -v63, v250, v35
	ds_read_b128 v[56:59], v176 offset:2592
	s_waitcnt lgkmcnt(10)
	v_fma_f32 v36, -v64, v250, v36
	v_fma_f32 v37, -v65, v250, v37
	v_fma_f32 v38, -v66, v250, v38
	v_fma_f32 v39, -v67, v250, v39
	ds_read_b128 v[60:63], v176 offset:2608
	s_waitcnt lgkmcnt(10)
	v_fma_f32 v40, -v68, v250, v40
	v_fma_f32 v41, -v69, v250, v41
	v_fma_f32 v42, -v70, v250, v42
	v_fma_f32 v43, -v71, v250, v43
	ds_read_b128 v[64:67], v176 offset:2816
	s_waitcnt lgkmcnt(10)
	v_fma_f32 v44, -v108, v250, v44
	v_fma_f32 v45, -v109, v250, v45
	v_fma_f32 v46, -v110, v250, v46
	v_fma_f32 v47, -v111, v250, v47
	ds_read_b128 v[68:71], v176 offset:2832
	v_mov_b32_dpp v254, v34 quad_perm:[1,1,1,1] row_mask:0xf bank_mask:0xf
	s_waitcnt lgkmcnt(10)
	v_fma_f32 v34, -v216, v254, v34
	v_fma_f32 v35, -v217, v254, v35
	ds_read_b128 v[108:111], v176 offset:2848
	s_waitcnt lgkmcnt(10)
	v_fma_f32 v36, -v218, v254, v36
	v_fma_f32 v37, -v219, v254, v37
	v_fma_f32 v38, -v220, v254, v38
	v_fma_f32 v39, -v221, v254, v39
	ds_read_b128 v[214:217], v176 offset:2864
	s_waitcnt lgkmcnt(10)
	v_fma_f32 v40, -v226, v254, v40
	v_fma_f32 v41, -v227, v254, v41
	v_fma_f32 v42, -v228, v254, v42
	v_fma_f32 v43, -v229, v254, v43
	ds_read_b128 v[218:221], v176 offset:3072
	s_waitcnt lgkmcnt(10)
	v_fma_f32 v44, -v230, v254, v44
	v_fma_f32 v45, -v231, v254, v45
	v_fma_f32 v46, -v232, v254, v46
	v_fma_f32 v47, -v233, v254, v47
	ds_read_b128 v[226:229], v176 offset:3088
	v_cvt_pk_bf16_f32 v252, v250, v254
	v_mov_b32_dpp v250, v34 quad_perm:[2,2,2,2] row_mask:0xf bank_mask:0xf
	s_waitcnt lgkmcnt(10)
	v_fma_f32 v34, -v50, v250, v34
	v_fma_f32 v35, -v51, v250, v35
	ds_read_b128 v[230:233], v176 offset:3104
	s_waitcnt lgkmcnt(10)
; #define LAS __attribute__((address_space(3)))
; template <int CTRL> __device__ __forceinline__ float dppf(float x) { return __builtin_bit_cast(float, __builtin_amdgcn_update_dpp(0, __builtin_bit_cast(int, x), CTRL, 0xf, 0xf, false)); }
; __device__ __forceinline__ u32x2 pack4(float a, float b, float c, float d) { u32x2 o; o.x = pk2(a, b); o.y = pk2(c, d); return o; }
; __device__ __forceinline__ void chunkA_item(const Args& A, LAS unsigned char* lds, int tid, int lane, int wave, int ci, int ci_next, HeadConstA& H) {
;     ...
;     if (tid < 256) {
;         const int cp = tid >> 2, q = tid & 3;
;         f32x2_t xa[8], xb[8];
; #pragma unroll
;         for (int m = 0; m < 8; ++m) { xa[m] = (f32x2_t){0.f, 0.f}; xb[m] = (f32x2_t){0.f, 0.f}; }
;         const LAS float* Np = (const LAS float*)(lds + CA_N) + q * 16;
;         const LAS float* Ra = (const LAS float*)(lds + CA_RHS) + cp * 68; const LAS float* Rb = Ra + 64 * 68;
;         float a4[4], b4[4];
; #pragma unroll
;         for (int t = 0; t < 64; ++t) {
;             f32x2_t sa = {0.f, 0.f}, sb = {0.f, 0.f};
; #pragma unroll
;             for (int p = 0; p < ((t + 3) / 4 + 1) / 2; ++p) { const f32x2_t nv = *(const LAS f32x2_t*)(Np + t * 64 + 2 * p); sa += nv * xa[p]; sb += nv * xb[p]; }
;             float ua = sa.x + sa.y, ub = sb.x + sb.y;
;             ua += dppf<0xB1>(ua); ub += dppf<0xB1>(ub); ua += dppf<0x4E>(ua); ub += dppf<0x4E>(ub);
;             const float xta = Ra[t] - ua, xtb = Rb[t] - ub;
;             if (q == (t & 3)) { if ((t >> 2) & 1) { xa[t >> 3].y = xta; xb[t >> 3].y = xtb; } else { xa[t >> 3].x = xta; xb[t >> 3].x = xtb; } }
;             a4[t & 3] = xta; b4[t & 3] = xtb;
;             if ((t & 3) == 3 && q == 0) { *(LAS u32x2*)(lds + CA_XT + cp * 144 + (t - 3) * 2) = pack4(a4[0], a4[1], a4[2], a4[3]);
;                 *(LAS u32x2*)(lds + CA_XT + (64 + cp) * 144 + (t - 3) * 2) = pack4(b4[0], b4[1], b4[2], b4[3]); }
;         }
	v_fma_f32 v36, -v52, v250, v36
	v_fma_f32 v37, -v53, v250, v37
	v_fma_f32 v38, -v54, v250, v38
	v_fma_f32 v39, -v55, v250, v39
	ds_read_b128 v[48:51], v176 offset:3120
	s_waitcnt lgkmcnt(9)
	v_fma_f32 v40, -v56, v250, v40
	v_fma_f32 v41, -v57, v250, v41
	v_fma_f32 v42, -v58, v250, v42
	v_fma_f32 v43, -v59, v250, v43
	ds_read_b128 v[52:55], v176 offset:3328
	s_waitcnt lgkmcnt(9)
	v_fma_f32 v44, -v60, v250, v44
	v_fma_f32 v45, -v61, v250, v45
	v_fma_f32 v46, -v62, v250, v46
	v_fma_f32 v47, -v63, v250, v47
	ds_read_b128 v[56:59], v176 offset:3344
	v_mov_b32_dpp v254, v34 quad_perm:[3,3,3,3] row_mask:0xf bank_mask:0xf
	s_waitcnt lgkmcnt(9)
	v_fma_f32 v34, -v66, v254, v34
	v_fma_f32 v35, -v67, v254, v35
	ds_read_b128 v[60:63], v176 offset:3360
	s_waitcnt lgkmcnt(9)
	v_fma_f32 v36, -v68, v254, v36
	v_fma_f32 v37, -v69, v254, v37
	v_fma_f32 v38, -v70, v254, v38
	v_fma_f32 v39, -v71, v254, v39
	ds_read_b128 v[64:67], v176 offset:3376
	s_waitcnt lgkmcnt(9)
	v_fma_f32 v40, -v108, v254, v40
	v_fma_f32 v41, -v109, v254, v41
	v_fma_f32 v42, -v110, v254, v42
	v_fma_f32 v43, -v111, v254, v43
	ds_read_b128 v[68:71], v176 offset:3584
	s_waitcnt lgkmcnt(9)
	v_fma_f32 v44, -v214, v254, v44
	v_fma_f32 v45, -v215, v254, v45
	v_fma_f32 v46, -v216, v254, v46
	v_fma_f32 v47, -v217, v254, v47
	ds_read_b128 v[108:111], v176 offset:3600
	v_cvt_pk_bf16_f32 v253, v250, v254
	s_mov_b64 exec, s[54:55]
	ds_write_b64 v202, v[252:253] offset:16
	s_mov_b64 exec, -1
	v_mov_b32_dpp v250, v35 quad_perm:[0,0,0,0] row_mask:0xf bank_mask:0xf
	s_waitcnt lgkmcnt(10)
	v_fma_f32 v34, -v220, v250, v34
	v_fma_f32 v35, -v221, v250, v35
	ds_read_b128 v[214:217], v176 offset:3616
	s_waitcnt lgkmcnt(10)
	v_fma_f32 v36, -v226, v250, v36
	v_fma_f32 v37, -v227, v250, v37
	v_fma_f32 v38, -v228, v250, v38
	v_fma_f32 v39, -v229, v250, v39
	ds_read_b128 v[218:221], v176 offset:3632
	s_waitcnt lgkmcnt(10)
	v_fma_f32 v40, -v230, v250, v40
	v_fma_f32 v41, -v231, v250, v41
	v_fma_f32 v42, -v232, v250, v42
	v_fma_f32 v43, -v233, v250, v43
	ds_read_b128 v[226:229], v176 offset:3840
	s_waitcnt lgkmcnt(10)
	v_fma_f32 v44, -v48, v250, v44
	v_fma_f32 v45, -v49, v250, v45
	v_fma_f32 v46, -v50, v250, v46
	v_fma_f32 v47, -v51, v250, v47
	ds_read_b128 v[230:233], v176 offset:3856
	v_mov_b32_dpp v254, v35 quad_perm:[1,1,1,1] row_mask:0xf bank_mask:0xf
	s_waitcnt lgkmcnt(10)
	v_fma_f32 v34, -v54, v254, v34
	v_fma_f32 v35, -v55, v254, v35
	ds_read_b128 v[48:51], v176 offset:3872
	s_waitcnt lgkmcnt(10)
	v_fma_f32 v36, -v56, v254, v36
	v_fma_f32 v37, -v57, v254, v37
	v_fma_f32 v38, -v58, v254, v38
	v_fma_f32 v39, -v59, v254, v39
	ds_read_b128 v[52:55], v176 offset:3888
	s_waitcnt lgkmcnt(10)
	v_fma_f32 v40, -v60, v254, v40
	v_fma_f32 v41, -v61, v254, v41
	v_fma_f32 v42, -v62, v254, v42
	v_fma_f32 v43, -v63, v254, v43
	ds_read_b128 v[56:59], v176 offset:4112
	s_waitcnt lgkmcnt(10)
	v_fma_f32 v44, -v64, v254, v44
	v_fma_f32 v45, -v65, v254, v45
	v_fma_f32 v46, -v66, v254, v46
	v_fma_f32 v47, -v67, v254, v47
	ds_read_b128 v[60:63], v176 offset:4128
	v_cvt_pk_bf16_f32 v252, v250, v254
	v_mov_b32_dpp v250, v35 quad_perm:[2,2,2,2] row_mask:0xf bank_mask:0xf
	s_waitcnt lgkmcnt(10)
	v_fma_f32 v34, -v70, v250, v34
	v_fma_f32 v35, -v71, v250, v35
	ds_read_b128 v[64:67], v176 offset:4144
	s_waitcnt lgkmcnt(10)
	v_fma_f32 v36, -v108, v250, v36
	v_fma_f32 v37, -v109, v250, v37
	v_fma_f32 v38, -v110, v250, v38
	v_fma_f32 v39, -v111, v250, v39
	ds_read_b128 v[68:71], v176 offset:4368
	s_waitcnt lgkmcnt(9)
	v_fma_f32 v40, -v214, v250, v40
	v_fma_f32 v41, -v215, v250, v41
	v_fma_f32 v42, -v216, v250, v42
	v_fma_f32 v43, -v217, v250, v43
	ds_read_b128 v[108:111], v176 offset:4384
	s_waitcnt lgkmcnt(9)
	v_fma_f32 v44, -v218, v250, v44
	v_fma_f32 v45, -v219, v250, v45
	v_fma_f32 v46, -v220, v250, v46
	v_fma_f32 v47, -v221, v250, v47
	ds_read_b128 v[214:217], v176 offset:4400
	v_mov_b32_dpp v254, v35 quad_perm:[3,3,3,3] row_mask:0xf bank_mask:0xf
	s_waitcnt lgkmcnt(9)
	v_fma_f32 v34, -v228, v254, v34
	v_fma_f32 v35, -v229, v254, v35
	ds_read_b128 v[218:221], v176 offset:4624
	s_waitcnt lgkmcnt(9)
	v_fma_f32 v36, -v230, v254, v36
	v_fma_f32 v37, -v231, v254, v37
	v_fma_f32 v38, -v232, v254, v38
	v_fma_f32 v39, -v233, v254, v39
	ds_read_b128 v[226:229], v176 offset:4640
	s_waitcnt lgkmcnt(9)
	v_fma_f32 v40, -v48, v254, v40
	v_fma_f32 v41, -v49, v254, v41
	v_fma_f32 v42, -v50, v254, v42
	v_fma_f32 v43, -v51, v254, v43
	ds_read_b128 v[230:233], v176 offset:4656
	s_waitcnt lgkmcnt(9)
	v_fma_f32 v44, -v52, v254, v44
	v_fma_f32 v45, -v53, v254, v45
	v_fma_f32 v46, -v54, v254, v46
	v_fma_f32 v47, -v55, v254, v47
	ds_read_b128 v[48:51], v176 offset:4880
	v_cvt_pk_bf16_f32 v253, v250, v254
	s_mov_b64 exec, s[54:55]
	ds_write_b64 v202, v[252:253] offset:24
	s_mov_b64 exec, -1
	v_mov_b32_dpp v250, v36 quad_perm:[0,0,0,0] row_mask:0xf bank_mask:0xf
	s_waitcnt lgkmcnt(10)
	v_fma_f32 v36, -v56, v250, v36
	v_fma_f32 v37, -v57, v250, v37
	v_fma_f32 v38, -v58, v250, v38
	v_fma_f32 v39, -v59, v250, v39
	ds_read_b128 v[52:55], v176 offset:4896
	s_waitcnt lgkmcnt(10)
	v_fma_f32 v40, -v60, v250, v40
	v_fma_f32 v41, -v61, v250, v41
	v_fma_f32 v42, -v62, v250, v42
	v_fma_f32 v43, -v63, v250, v43
	ds_read_b128 v[56:59], v176 offset:4912
	s_waitcnt lgkmcnt(10)
	v_fma_f32 v44, -v64, v250, v44
	v_fma_f32 v45, -v65, v250, v45
	v_fma_f32 v46, -v66, v250, v46
	v_fma_f32 v47, -v67, v250, v47
	ds_read_b128 v[60:63], v176 offset:5136
	v_mov_b32_dpp v254, v36 quad_perm:[1,1,1,1] row_mask:0xf bank_mask:0xf
	s_waitcnt lgkmcnt(10)
	v_fma_f32 v36, -v68, v254, v36
	v_fma_f32 v37, -v69, v254, v37
	v_fma_f32 v38, -v70, v254, v38
	v_fma_f32 v39, -v71, v254, v39
	ds_read_b128 v[64:67], v176 offset:5152
	s_waitcnt lgkmcnt(10)
; #define LAS __attribute__((address_space(3)))
; template <int CTRL> __device__ __forceinline__ float dppf(float x) { return __builtin_bit_cast(float, __builtin_amdgcn_update_dpp(0, __builtin_bit_cast(int, x), CTRL, 0xf, 0xf, false)); }
; __device__ __forceinline__ u32x2 pack4(float a, float b, float c, float d) { u32x2 o; o.x = pk2(a, b); o.y = pk2(c, d); return o; }
; __device__ __forceinline__ void chunkA_item(const Args& A, LAS unsigned char* lds, int tid, int lane, int wave, int ci, int ci_next, HeadConstA& H) {
;     ...
;     if (tid < 256) {
;         const int cp = tid >> 2, q = tid & 3;
;         f32x2_t xa[8], xb[8];
; #pragma unroll
;         for (int m = 0; m < 8; ++m) { xa[m] = (f32x2_t){0.f, 0.f}; xb[m] = (f32x2_t){0.f, 0.f}; }
;         const LAS float* Np = (const LAS float*)(lds + CA_N) + q * 16;
;         const LAS float* Ra = (const LAS float*)(lds + CA_RHS) + cp * 68; const LAS float* Rb = Ra + 64 * 68;
;         float a4[4], b4[4];
; #pragma unroll
;         for (int t = 0; t < 64; ++t) {
;             f32x2_t sa = {0.f, 0.f}, sb = {0.f, 0.f};
; #pragma unroll
;             for (int p = 0; p < ((t + 3) / 4 + 1) / 2; ++p) { const f32x2_t nv = *(const LAS f32x2_t*)(Np + t * 64 + 2 * p); sa += nv * xa[p]; sb += nv * xb[p]; }
;             float ua = sa.x + sa.y, ub = sb.x + sb.y;
;             ua += dppf<0xB1>(ua); ub += dppf<0xB1>(ub); ua += dppf<0x4E>(ua); ub += dppf<0x4E>(ub);
;             const float xta = Ra[t] - ua, xtb = Rb[t] - ub;
;             if (q == (t & 3)) { if ((t >> 2) & 1) { xa[t >> 3].y = xta; xb[t >> 3].y = xtb; } else { xa[t >> 3].x = xta; xb[t >> 3].x = xtb; } }
;             a4[t & 3] = xta; b4[t & 3] = xtb;
;             if ((t & 3) == 3 && q == 0) { *(LAS u32x2*)(lds + CA_XT + cp * 144 + (t - 3) * 2) = pack4(a4[0], a4[1], a4[2], a4[3]);
;                 *(LAS u32x2*)(lds + CA_XT + (64 + cp) * 144 + (t - 3) * 2) = pack4(b4[0], b4[1], b4[2], b4[3]); }
;         }
	v_fma_f32 v40, -v108, v254, v40
	v_fma_f32 v41, -v109, v254, v41
	v_fma_f32 v42, -v110, v254, v42
	v_fma_f32 v43, -v111, v254, v43
	ds_read_b128 v[68:71], v176 offset:5168
	s_waitcnt lgkmcnt(10)
	v_fma_f32 v44, -v214, v254, v44
	v_fma_f32 v45, -v215, v254, v45
	v_fma_f32 v46, -v216, v254, v46
	v_fma_f32 v47, -v217, v254, v47
	ds_read_b128 v[108:111], v176 offset:5392
	v_cvt_pk_bf16_f32 v252, v250, v254
	v_mov_b32_dpp v250, v36 quad_perm:[2,2,2,2] row_mask:0xf bank_mask:0xf
	s_waitcnt lgkmcnt(10)
	v_fma_f32 v36, -v218, v250, v36
	v_fma_f32 v37, -v219, v250, v37
	v_fma_f32 v38, -v220, v250, v38
	v_fma_f32 v39, -v221, v250, v39
	ds_read_b128 v[214:217], v176 offset:5408
	s_waitcnt lgkmcnt(10)
	v_fma_f32 v40, -v226, v250, v40
	v_fma_f32 v41, -v227, v250, v41
	v_fma_f32 v42, -v228, v250, v42
	v_fma_f32 v43, -v229, v250, v43
	ds_read_b128 v[218:221], v176 offset:5424
	s_waitcnt lgkmcnt(10)
	v_fma_f32 v44, -v230, v250, v44
	v_fma_f32 v45, -v231, v250, v45
	v_fma_f32 v46, -v232, v250, v46
	v_fma_f32 v47, -v233, v250, v47
	ds_read_b128 v[226:229], v176 offset:5648
	v_mov_b32_dpp v254, v36 quad_perm:[3,3,3,3] row_mask:0xf bank_mask:0xf
	s_waitcnt lgkmcnt(10)
	v_fma_f32 v36, -v48, v254, v36
	v_fma_f32 v37, -v49, v254, v37
	v_fma_f32 v38, -v50, v254, v38
	v_fma_f32 v39, -v51, v254, v39
	ds_read_b128 v[230:233], v176 offset:5664
	s_waitcnt lgkmcnt(9)
	v_fma_f32 v40, -v52, v254, v40
	v_fma_f32 v41, -v53, v254, v41
	v_fma_f32 v42, -v54, v254, v42
	v_fma_f32 v43, -v55, v254, v43
	ds_read_b128 v[48:51], v176 offset:5680
	s_waitcnt lgkmcnt(9)
	v_fma_f32 v44, -v56, v254, v44
	v_fma_f32 v45, -v57, v254, v45
	v_fma_f32 v46, -v58, v254, v46
	v_fma_f32 v47, -v59, v254, v47
	ds_read_b128 v[52:55], v176 offset:5904
	v_cvt_pk_bf16_f32 v253, v250, v254
	s_mov_b64 exec, s[54:55]
	ds_write_b64 v202, v[252:253] offset:32
	s_mov_b64 exec, -1
	v_mov_b32_dpp v250, v37 quad_perm:[0,0,0,0] row_mask:0xf bank_mask:0xf
	s_waitcnt lgkmcnt(10)
	v_fma_f32 v36, -v60, v250, v36
	v_fma_f32 v37, -v61, v250, v37
	v_fma_f32 v38, -v62, v250, v38
	v_fma_f32 v39, -v63, v250, v39
	ds_read_b128 v[56:59], v176 offset:5920
	s_waitcnt lgkmcnt(10)
	v_fma_f32 v40, -v64, v250, v40
	v_fma_f32 v41, -v65, v250, v41
	v_fma_f32 v42, -v66, v250, v42
	v_fma_f32 v43, -v67, v250, v43
	ds_read_b128 v[60:63], v176 offset:5936
	s_waitcnt lgkmcnt(10)
	v_fma_f32 v44, -v68, v250, v44
	v_fma_f32 v45, -v69, v250, v45
	v_fma_f32 v46, -v70, v250, v46
	v_fma_f32 v47, -v71, v250, v47
	ds_read_b128 v[64:67], v176 offset:6160
	v_mov_b32_dpp v254, v37 quad_perm:[1,1,1,1] row_mask:0xf bank_mask:0xf
	s_waitcnt lgkmcnt(10)
	v_fma_f32 v36, -v108, v254, v36
	v_fma_f32 v37, -v109, v254, v37
	v_fma_f32 v38, -v110, v254, v38
	v_fma_f32 v39, -v111, v254, v39
	ds_read_b128 v[68:71], v176 offset:6176
	s_waitcnt lgkmcnt(10)
	v_fma_f32 v40, -v214, v254, v40
	v_fma_f32 v41, -v215, v254, v41
	v_fma_f32 v42, -v216, v254, v42
	v_fma_f32 v43, -v217, v254, v43
	ds_read_b128 v[108:111], v176 offset:6192
	s_waitcnt lgkmcnt(10)
	v_fma_f32 v44, -v218, v254, v44
	v_fma_f32 v45, -v219, v254, v45
	v_fma_f32 v46, -v220, v254, v46
	v_fma_f32 v47, -v221, v254, v47
	ds_read_b128 v[214:217], v176 offset:6416
	v_cvt_pk_bf16_f32 v252, v250, v254
	v_mov_b32_dpp v250, v37 quad_perm:[2,2,2,2] row_mask:0xf bank_mask:0xf
	s_waitcnt lgkmcnt(10)
	v_fma_f32 v36, -v226, v250, v36
	v_fma_f32 v37, -v227, v250, v37
	v_fma_f32 v38, -v228, v250, v38
	v_fma_f32 v39, -v229, v250, v39
	ds_read_b128 v[218:221], v176 offset:6432
	s_waitcnt lgkmcnt(10)
	v_fma_f32 v40, -v230, v250, v40
	v_fma_f32 v41, -v231, v250, v41
	v_fma_f32 v42, -v232, v250, v42
	v_fma_f32 v43, -v233, v250, v43
	ds_read_b128 v[226:229], v176 offset:6448
	s_waitcnt lgkmcnt(10)
	v_fma_f32 v44, -v48, v250, v44
	v_fma_f32 v45, -v49, v250, v45
	v_fma_f32 v46, -v50, v250, v46
	v_fma_f32 v47, -v51, v250, v47
	ds_read_b128 v[230:233], v176 offset:6672
	v_mov_b32_dpp v254, v37 quad_perm:[3,3,3,3] row_mask:0xf bank_mask:0xf
	s_waitcnt lgkmcnt(10)
	v_fma_f32 v38, -v54, v254, v38
	v_fma_f32 v39, -v55, v254, v39
	v_fma_f32 v36, -v52, v254, v36
	v_fma_f32 v37, -v53, v254, v37
	ds_read_b128 v[48:51], v176 offset:6688
	s_waitcnt lgkmcnt(9)
	v_fma_f32 v40, -v56, v254, v40
	v_fma_f32 v41, -v57, v254, v41
	v_fma_f32 v42, -v58, v254, v42
	v_fma_f32 v43, -v59, v254, v43
	ds_read_b128 v[52:55], v176 offset:6704
	s_waitcnt lgkmcnt(9)
	v_fma_f32 v44, -v60, v254, v44
	v_fma_f32 v45, -v61, v254, v45
	v_fma_f32 v46, -v62, v254, v46
	v_fma_f32 v47, -v63, v254, v47
	ds_read_b128 v[56:59], v176 offset:6928
	v_cvt_pk_bf16_f32 v253, v250, v254
	s_mov_b64 exec, s[54:55]
	ds_write_b64 v202, v[252:253] offset:40
	s_mov_b64 exec, -1
	v_mov_b32_dpp v250, v38 quad_perm:[0,0,0,0] row_mask:0xf bank_mask:0xf
	s_waitcnt lgkmcnt(10)
	v_fma_f32 v38, -v66, v250, v38
	v_fma_f32 v39, -v67, v250, v39
	ds_read_b128 v[60:63], v176 offset:6944
	s_waitcnt lgkmcnt(10)
	v_fma_f32 v40, -v68, v250, v40
	v_fma_f32 v41, -v69, v250, v41
	v_fma_f32 v42, -v70, v250, v42
	v_fma_f32 v43, -v71, v250, v43
	ds_read_b128 v[64:67], v176 offset:6960
	s_waitcnt lgkmcnt(10)
	v_fma_f32 v44, -v108, v250, v44
	v_fma_f32 v45, -v109, v250, v45
	v_fma_f32 v46, -v110, v250, v46
	v_fma_f32 v47, -v111, v250, v47
	ds_read_b128 v[68:71], v176 offset:7184
	v_mov_b32_dpp v254, v38 quad_perm:[1,1,1,1] row_mask:0xf bank_mask:0xf
	s_waitcnt lgkmcnt(10)
	v_fma_f32 v38, -v216, v254, v38
	v_fma_f32 v39, -v217, v254, v39
	ds_read_b128 v[108:111], v176 offset:7200
	s_waitcnt lgkmcnt(10)
	v_fma_f32 v40, -v218, v254, v40
	v_fma_f32 v41, -v219, v254, v41
	v_fma_f32 v42, -v220, v254, v42
	v_fma_f32 v43, -v221, v254, v43
	ds_read_b128 v[214:217], v176 offset:7216
	s_waitcnt lgkmcnt(10)
; #define LAS __attribute__((address_space(3)))
; template <int CTRL> __device__ __forceinline__ float dppf(float x) { return __builtin_bit_cast(float, __builtin_amdgcn_update_dpp(0, __builtin_bit_cast(int, x), CTRL, 0xf, 0xf, false)); }
; __device__ __forceinline__ u32x2 pack4(float a, float b, float c, float d) { u32x2 o; o.x = pk2(a, b); o.y = pk2(c, d); return o; }
; __device__ __forceinline__ void chunkA_item(const Args& A, LAS unsigned char* lds, int tid, int lane, int wave, int ci, int ci_next, HeadConstA& H) {
;     ...
;     if (tid < 256) {
;         const int cp = tid >> 2, q = tid & 3;
;         f32x2_t xa[8], xb[8];
; #pragma unroll
;         for (int m = 0; m < 8; ++m) { xa[m] = (f32x2_t){0.f, 0.f}; xb[m] = (f32x2_t){0.f, 0.f}; }
;         const LAS float* Np = (const LAS float*)(lds + CA_N) + q * 16;
;         const LAS float* Ra = (const LAS float*)(lds + CA_RHS) + cp * 68; const LAS float* Rb = Ra + 64 * 68;
;         float a4[4], b4[4];
; #pragma unroll
;         for (int t = 0; t < 64; ++t) {
;             f32x2_t sa = {0.f, 0.f}, sb = {0.f, 0.f};
; #pragma unroll
;             for (int p = 0; p < ((t + 3) / 4 + 1) / 2; ++p) { const f32x2_t nv = *(const LAS f32x2_t*)(Np + t * 64 + 2 * p); sa += nv * xa[p]; sb += nv * xb[p]; }
;             float ua = sa.x + sa.y, ub = sb.x + sb.y;
;             ua += dppf<0xB1>(ua); ub += dppf<0xB1>(ub); ua += dppf<0x4E>(ua); ub += dppf<0x4E>(ub);
;             const float xta = Ra[t] - ua, xtb = Rb[t] - ub;
;             if (q == (t & 3)) { if ((t >> 2) & 1) { xa[t >> 3].y = xta; xb[t >> 3].y = xtb; } else { xa[t >> 3].x = xta; xb[t >> 3].x = xtb; } }
;             a4[t & 3] = xta; b4[t & 3] = xtb;
;             if ((t & 3) == 3 && q == 0) { *(LAS u32x2*)(lds + CA_XT + cp * 144 + (t - 3) * 2) = pack4(a4[0], a4[1], a4[2], a4[3]);
;                 *(LAS u32x2*)(lds + CA_XT + (64 + cp) * 144 + (t - 3) * 2) = pack4(b4[0], b4[1], b4[2], b4[3]); }
;         }
	v_fma_f32 v44, -v226, v254, v44
	v_fma_f32 v45, -v227, v254, v45
	v_fma_f32 v46, -v228, v254, v46
	v_fma_f32 v47, -v229, v254, v47
	ds_read_b128 v[218:221], v176 offset:7440
	v_cvt_pk_bf16_f32 v252, v250, v254
	v_mov_b32_dpp v250, v38 quad_perm:[2,2,2,2] row_mask:0xf bank_mask:0xf
	s_waitcnt lgkmcnt(10)
	v_fma_f32 v38, -v232, v250, v38
	v_fma_f32 v39, -v233, v250, v39
	ds_read_b128 v[226:229], v176 offset:7456
	s_waitcnt lgkmcnt(10)
	v_fma_f32 v40, -v48, v250, v40
	v_fma_f32 v41, -v49, v250, v41
	v_fma_f32 v42, -v50, v250, v42
	v_fma_f32 v43, -v51, v250, v43
	ds_read_b128 v[230:233], v176 offset:7472
	s_waitcnt lgkmcnt(10)
	v_fma_f32 v44, -v52, v250, v44
	v_fma_f32 v45, -v53, v250, v45
	v_fma_f32 v46, -v54, v250, v46
	v_fma_f32 v47, -v55, v250, v47
	ds_read_b128 v[48:51], v176 offset:7696
	v_mov_b32_dpp v254, v38 quad_perm:[3,3,3,3] row_mask:0xf bank_mask:0xf
	s_waitcnt lgkmcnt(10)
	v_fma_f32 v38, -v58, v254, v38
	v_fma_f32 v39, -v59, v254, v39
	ds_read_b128 v[52:55], v176 offset:7712
	s_waitcnt lgkmcnt(9)
	v_fma_f32 v40, -v60, v254, v40
	v_fma_f32 v41, -v61, v254, v41
	v_fma_f32 v42, -v62, v254, v42
	v_fma_f32 v43, -v63, v254, v43
	ds_read_b128 v[56:59], v176 offset:7728
	s_waitcnt lgkmcnt(9)
	v_fma_f32 v44, -v64, v254, v44
	v_fma_f32 v45, -v65, v254, v45
	v_fma_f32 v46, -v66, v254, v46
	v_fma_f32 v47, -v67, v254, v47
	ds_read_b128 v[60:63], v176 offset:7952
	v_cvt_pk_bf16_f32 v253, v250, v254
	s_mov_b64 exec, s[54:55]
	ds_write_b64 v202, v[252:253] offset:48
	s_mov_b64 exec, -1
	v_mov_b32_dpp v250, v39 quad_perm:[0,0,0,0] row_mask:0xf bank_mask:0xf
	s_waitcnt lgkmcnt(10)
	v_fma_f32 v38, -v70, v250, v38
	v_fma_f32 v39, -v71, v250, v39
	ds_read_b128 v[64:67], v176 offset:7968
	s_waitcnt lgkmcnt(10)
	v_fma_f32 v40, -v108, v250, v40
	v_fma_f32 v41, -v109, v250, v41
	v_fma_f32 v42, -v110, v250, v42
	v_fma_f32 v43, -v111, v250, v43
	ds_read_b128 v[68:71], v176 offset:7984
	s_waitcnt lgkmcnt(10)
	v_fma_f32 v44, -v214, v250, v44
	v_fma_f32 v45, -v215, v250, v45
	v_fma_f32 v46, -v216, v250, v46
	v_fma_f32 v47, -v217, v250, v47
	ds_read_b128 v[108:111], v176 offset:8224
	v_mov_b32_dpp v254, v39 quad_perm:[1,1,1,1] row_mask:0xf bank_mask:0xf
	s_waitcnt lgkmcnt(10)
	v_fma_f32 v38, -v220, v254, v38
	v_fma_f32 v39, -v221, v254, v39
	ds_read_b128 v[214:217], v176 offset:8240
	s_waitcnt lgkmcnt(10)
	v_fma_f32 v40, -v226, v254, v40
	v_fma_f32 v41, -v227, v254, v41
	v_fma_f32 v42, -v228, v254, v42
	v_fma_f32 v43, -v229, v254, v43
	ds_read_b128 v[218:221], v176 offset:8480
	s_waitcnt lgkmcnt(10)
	v_fma_f32 v44, -v230, v254, v44
	v_fma_f32 v45, -v231, v254, v45
	v_fma_f32 v46, -v232, v254, v46
	v_fma_f32 v47, -v233, v254, v47
	ds_read_b128 v[226:229], v176 offset:8496
	v_cvt_pk_bf16_f32 v252, v250, v254
	v_mov_b32_dpp v250, v39 quad_perm:[2,2,2,2] row_mask:0xf bank_mask:0xf
	s_waitcnt lgkmcnt(10)
	v_fma_f32 v38, -v50, v250, v38
	v_fma_f32 v39, -v51, v250, v39
	ds_read_b128 v[230:233], v176 offset:8736
	s_waitcnt lgkmcnt(10)
	v_fma_f32 v40, -v52, v250, v40
	v_fma_f32 v41, -v53, v250, v41
	v_fma_f32 v42, -v54, v250, v42
	v_fma_f32 v43, -v55, v250, v43
	ds_read_b128 v[48:51], v176 offset:8752
	s_waitcnt lgkmcnt(10)
	v_fma_f32 v44, -v56, v250, v44
	v_fma_f32 v45, -v57, v250, v45
	v_fma_f32 v46, -v58, v250, v46
	v_fma_f32 v47, -v59, v250, v47
	ds_read_b128 v[52:55], v176 offset:8992
	v_mov_b32_dpp v254, v39 quad_perm:[3,3,3,3] row_mask:0xf bank_mask:0xf
	s_waitcnt lgkmcnt(10)
	v_fma_f32 v38, -v62, v254, v38
	v_fma_f32 v39, -v63, v254, v39
	ds_read_b128 v[56:59], v176 offset:9008
	s_waitcnt lgkmcnt(9)
	v_fma_f32 v40, -v64, v254, v40
	v_fma_f32 v41, -v65, v254, v41
	v_fma_f32 v42, -v66, v254, v42
	v_fma_f32 v43, -v67, v254, v43
	ds_read_b128 v[60:63], v176 offset:9248
	s_waitcnt lgkmcnt(9)
	v_fma_f32 v44, -v68, v254, v44
	v_fma_f32 v45, -v69, v254, v45
	v_fma_f32 v46, -v70, v254, v46
	v_fma_f32 v47, -v71, v254, v47
	ds_read_b128 v[64:67], v176 offset:9264
	v_cvt_pk_bf16_f32 v253, v250, v254
	s_mov_b64 exec, s[54:55]
	ds_write_b64 v202, v[252:253] offset:56
	s_mov_b64 exec, -1
	v_mov_b32_dpp v250, v40 quad_perm:[0,0,0,0] row_mask:0xf bank_mask:0xf
	s_waitcnt lgkmcnt(10)
	v_fma_f32 v40, -v108, v250, v40
	v_fma_f32 v41, -v109, v250, v41
	v_fma_f32 v42, -v110, v250, v42
	v_fma_f32 v43, -v111, v250, v43
	ds_read_b128 v[68:71], v176 offset:9504
	s_waitcnt lgkmcnt(10)
	v_fma_f32 v44, -v214, v250, v44
	v_fma_f32 v45, -v215, v250, v45
	v_fma_f32 v46, -v216, v250, v46
	v_fma_f32 v47, -v217, v250, v47
	ds_read_b128 v[108:111], v176 offset:9520
	v_mov_b32_dpp v254, v40 quad_perm:[1,1,1,1] row_mask:0xf bank_mask:0xf
	s_waitcnt lgkmcnt(10)
	v_fma_f32 v40, -v218, v254, v40
	v_fma_f32 v41, -v219, v254, v41
	v_fma_f32 v42, -v220, v254, v42
	v_fma_f32 v43, -v221, v254, v43
	ds_read_b128 v[214:217], v176 offset:9760
	s_waitcnt lgkmcnt(10)
	v_fma_f32 v44, -v226, v254, v44
	v_fma_f32 v45, -v227, v254, v45
	v_fma_f32 v46, -v228, v254, v46
	v_fma_f32 v47, -v229, v254, v47
	ds_read_b128 v[218:221], v176 offset:9776
	v_cvt_pk_bf16_f32 v252, v250, v254
	v_mov_b32_dpp v250, v40 quad_perm:[2,2,2,2] row_mask:0xf bank_mask:0xf
	s_waitcnt lgkmcnt(10)
	v_fma_f32 v40, -v230, v250, v40
	v_fma_f32 v41, -v231, v250, v41
	v_fma_f32 v42, -v232, v250, v42
	v_fma_f32 v43, -v233, v250, v43
	ds_read_b128 v[226:229], v176 offset:10016
	s_waitcnt lgkmcnt(10)
	v_fma_f32 v44, -v48, v250, v44
	v_fma_f32 v45, -v49, v250, v45
	v_fma_f32 v46, -v50, v250, v46
	v_fma_f32 v47, -v51, v250, v47
	ds_read_b128 v[230:233], v176 offset:10032
	v_mov_b32_dpp v254, v40 quad_perm:[3,3,3,3] row_mask:0xf bank_mask:0xf
	s_waitcnt lgkmcnt(10)
; #define LAS __attribute__((address_space(3)))
; template <int CTRL> __device__ __forceinline__ float dppf(float x) { return __builtin_bit_cast(float, __builtin_amdgcn_update_dpp(0, __builtin_bit_cast(int, x), CTRL, 0xf, 0xf, false)); }
; __device__ __forceinline__ u32x2 pack4(float a, float b, float c, float d) { u32x2 o; o.x = pk2(a, b); o.y = pk2(c, d); return o; }
; __device__ __forceinline__ void chunkA_item(const Args& A, LAS unsigned char* lds, int tid, int lane, int wave, int ci, int ci_next, HeadConstA& H) {
;     ...
;     if (tid < 256) {
;         const int cp = tid >> 2, q = tid & 3;
;         f32x2_t xa[8], xb[8];
; #pragma unroll
;         for (int m = 0; m < 8; ++m) { xa[m] = (f32x2_t){0.f, 0.f}; xb[m] = (f32x2_t){0.f, 0.f}; }
;         const LAS float* Np = (const LAS float*)(lds + CA_N) + q * 16;
;         const LAS float* Ra = (const LAS float*)(lds + CA_RHS) + cp * 68; const LAS float* Rb = Ra + 64 * 68;
;         float a4[4], b4[4];
; #pragma unroll
;         for (int t = 0; t < 64; ++t) {
;             f32x2_t sa = {0.f, 0.f}, sb = {0.f, 0.f};
; #pragma unroll
;             for (int p = 0; p < ((t + 3) / 4 + 1) / 2; ++p) { const f32x2_t nv = *(const LAS f32x2_t*)(Np + t * 64 + 2 * p); sa += nv * xa[p]; sb += nv * xb[p]; }
;             float ua = sa.x + sa.y, ub = sb.x + sb.y;
;             ua += dppf<0xB1>(ua); ub += dppf<0xB1>(ub); ua += dppf<0x4E>(ua); ub += dppf<0x4E>(ub);
;             const float xta = Ra[t] - ua, xtb = Rb[t] - ub;
;             if (q == (t & 3)) { if ((t >> 2) & 1) { xa[t >> 3].y = xta; xb[t >> 3].y = xtb; } else { xa[t >> 3].x = xta; xb[t >> 3].x = xtb; } }
;             a4[t & 3] = xta; b4[t & 3] = xtb;
;             if ((t & 3) == 3 && q == 0) { *(LAS u32x2*)(lds + CA_XT + cp * 144 + (t - 3) * 2) = pack4(a4[0], a4[1], a4[2], a4[3]);
;                 *(LAS u32x2*)(lds + CA_XT + (64 + cp) * 144 + (t - 3) * 2) = pack4(b4[0], b4[1], b4[2], b4[3]); }
;         }
	v_fma_f32 v40, -v52, v254, v40
	v_fma_f32 v41, -v53, v254, v41
	v_fma_f32 v42, -v54, v254, v42
	v_fma_f32 v43, -v55, v254, v43
	ds_read_b128 v[48:51], v176 offset:10272
	s_waitcnt lgkmcnt(10)
	v_fma_f32 v44, -v56, v254, v44
	v_fma_f32 v45, -v57, v254, v45
	v_fma_f32 v46, -v58, v254, v46
	v_fma_f32 v47, -v59, v254, v47
	ds_read_b128 v[52:55], v176 offset:10288
	v_cvt_pk_bf16_f32 v253, v250, v254
	s_mov_b64 exec, s[54:55]
	ds_write_b64 v202, v[252:253] offset:64
	s_mov_b64 exec, -1
	v_mov_b32_dpp v250, v41 quad_perm:[0,0,0,0] row_mask:0xf bank_mask:0xf
	s_waitcnt lgkmcnt(11)
	v_fma_f32 v40, -v60, v250, v40
	v_fma_f32 v41, -v61, v250, v41
	v_fma_f32 v42, -v62, v250, v42
	v_fma_f32 v43, -v63, v250, v43
	ds_read_b128 v[56:59], v176 offset:10528
	s_waitcnt lgkmcnt(11)
	v_fma_f32 v44, -v64, v250, v44
	v_fma_f32 v45, -v65, v250, v45
	v_fma_f32 v46, -v66, v250, v46
	v_fma_f32 v47, -v67, v250, v47
	ds_read_b128 v[60:63], v176 offset:10544
	v_mov_b32_dpp v254, v41 quad_perm:[1,1,1,1] row_mask:0xf bank_mask:0xf
	s_waitcnt lgkmcnt(10)
	v_fma_f32 v40, -v68, v254, v40
	v_fma_f32 v41, -v69, v254, v41
	v_fma_f32 v42, -v70, v254, v42
	v_fma_f32 v43, -v71, v254, v43
	ds_read_b128 v[64:67], v176 offset:10784
	s_waitcnt lgkmcnt(10)
	v_fma_f32 v44, -v108, v254, v44
	v_fma_f32 v45, -v109, v254, v45
	v_fma_f32 v46, -v110, v254, v46
	v_fma_f32 v47, -v111, v254, v47
	ds_read_b128 v[68:71], v176 offset:10800
	v_cvt_pk_bf16_f32 v252, v250, v254
	v_mov_b32_dpp v250, v41 quad_perm:[2,2,2,2] row_mask:0xf bank_mask:0xf
	s_waitcnt lgkmcnt(10)
	v_fma_f32 v40, -v214, v250, v40
	v_fma_f32 v41, -v215, v250, v41
	v_fma_f32 v42, -v216, v250, v42
	v_fma_f32 v43, -v217, v250, v43
	ds_read_b128 v[108:111], v176 offset:11040
	s_waitcnt lgkmcnt(10)
	v_fma_f32 v44, -v218, v250, v44
	v_fma_f32 v45, -v219, v250, v45
	v_fma_f32 v46, -v220, v250, v46
	v_fma_f32 v47, -v221, v250, v47
	ds_read_b128 v[214:217], v176 offset:11056
	v_mov_b32_dpp v254, v41 quad_perm:[3,3,3,3] row_mask:0xf bank_mask:0xf
	s_waitcnt lgkmcnt(10)
	v_fma_f32 v42, -v228, v254, v42
	v_fma_f32 v43, -v229, v254, v43
	v_fma_f32 v40, -v226, v254, v40
	v_fma_f32 v41, -v227, v254, v41
	ds_read_b128 v[218:221], v176 offset:11296
	s_waitcnt lgkmcnt(10)
	v_fma_f32 v44, -v230, v254, v44
	v_fma_f32 v45, -v231, v254, v45
	v_fma_f32 v46, -v232, v254, v46
	v_fma_f32 v47, -v233, v254, v47
	ds_read_b128 v[226:229], v176 offset:11312
	v_cvt_pk_bf16_f32 v253, v250, v254
	s_mov_b64 exec, s[54:55]
	ds_write_b64 v202, v[252:253] offset:72
	s_mov_b64 exec, -1
	v_mov_b32_dpp v250, v42 quad_perm:[0,0,0,0] row_mask:0xf bank_mask:0xf
	s_waitcnt lgkmcnt(11)
	v_fma_f32 v42, -v50, v250, v42
	v_fma_f32 v43, -v51, v250, v43
	ds_read_b128 v[230:233], v176 offset:11552
	s_waitcnt lgkmcnt(11)
	v_fma_f32 v44, -v52, v250, v44
	v_fma_f32 v45, -v53, v250, v45
	v_fma_f32 v46, -v54, v250, v46
	v_fma_f32 v47, -v55, v250, v47
	ds_read_b128 v[48:51], v176 offset:11568
	v_mov_b32_dpp v254, v42 quad_perm:[1,1,1,1] row_mask:0xf bank_mask:0xf
	s_waitcnt lgkmcnt(10)
	v_fma_f32 v42, -v58, v254, v42
	v_fma_f32 v43, -v59, v254, v43
	ds_read_b128 v[52:55], v176 offset:11808
	s_waitcnt lgkmcnt(10)
	v_fma_f32 v44, -v60, v254, v44
	v_fma_f32 v45, -v61, v254, v45
	v_fma_f32 v46, -v62, v254, v46
	v_fma_f32 v47, -v63, v254, v47
	ds_read_b128 v[56:59], v176 offset:11824
	v_cvt_pk_bf16_f32 v252, v250, v254
	v_mov_b32_dpp v250, v42 quad_perm:[2,2,2,2] row_mask:0xf bank_mask:0xf
	s_waitcnt lgkmcnt(10)
	v_fma_f32 v42, -v66, v250, v42
	v_fma_f32 v43, -v67, v250, v43
	ds_read_b128 v[60:63], v176 offset:12064
	s_waitcnt lgkmcnt(10)
	v_fma_f32 v44, -v68, v250, v44
	v_fma_f32 v45, -v69, v250, v45
	v_fma_f32 v46, -v70, v250, v46
	v_fma_f32 v47, -v71, v250, v47
	ds_read_b128 v[64:67], v176 offset:12080
	v_mov_b32_dpp v254, v42 quad_perm:[3,3,3,3] row_mask:0xf bank_mask:0xf
	s_waitcnt lgkmcnt(10)
	v_fma_f32 v42, -v110, v254, v42
	v_fma_f32 v43, -v111, v254, v43
	ds_read_b128 v[68:71], v176 offset:12336
	s_waitcnt lgkmcnt(10)
	v_fma_f32 v44, -v214, v254, v44
	v_fma_f32 v45, -v215, v254, v45
	v_fma_f32 v46, -v216, v254, v46
	v_fma_f32 v47, -v217, v254, v47
	ds_read_b128 v[108:111], v176 offset:12592
	v_cvt_pk_bf16_f32 v253, v250, v254
	s_mov_b64 exec, s[54:55]
	ds_write_b64 v202, v[252:253] offset:80
	s_mov_b64 exec, -1
	v_mov_b32_dpp v250, v43 quad_perm:[0,0,0,0] row_mask:0xf bank_mask:0xf
	s_waitcnt lgkmcnt(11)
	v_fma_f32 v42, -v220, v250, v42
	v_fma_f32 v43, -v221, v250, v43
	ds_read_b128 v[214:217], v176 offset:12848
	s_waitcnt lgkmcnt(11)
	v_fma_f32 v44, -v226, v250, v44
	v_fma_f32 v45, -v227, v250, v45
	v_fma_f32 v46, -v228, v250, v46
	v_fma_f32 v47, -v229, v250, v47
	ds_read_b128 v[218:221], v176 offset:13104
	v_mov_b32_dpp v254, v43 quad_perm:[1,1,1,1] row_mask:0xf bank_mask:0xf
	s_waitcnt lgkmcnt(10)
	v_fma_f32 v42, -v232, v254, v42
	v_fma_f32 v43, -v233, v254, v43
	ds_read_b128 v[226:229], v176 offset:13360
	s_waitcnt lgkmcnt(10)
; #define LAS __attribute__((address_space(3)))
; template <int CTRL> __device__ __forceinline__ float dppf(float x) { return __builtin_bit_cast(float, __builtin_amdgcn_update_dpp(0, __builtin_bit_cast(int, x), CTRL, 0xf, 0xf, false)); }
; __device__ __forceinline__ u32x2 pack4(float a, float b, float c, float d) { u32x2 o; o.x = pk2(a, b); o.y = pk2(c, d); return o; }
; __device__ __forceinline__ void chunkA_item(const Args& A, LAS unsigned char* lds, int tid, int lane, int wave, int ci, int ci_next, HeadConstA& H) {
;     ...
;     if (tid < 256) {
;         const int cp = tid >> 2, q = tid & 3;
;         f32x2_t xa[8], xb[8];
; #pragma unroll
;         for (int m = 0; m < 8; ++m) { xa[m] = (f32x2_t){0.f, 0.f}; xb[m] = (f32x2_t){0.f, 0.f}; }
;         const LAS float* Np = (const LAS float*)(lds + CA_N) + q * 16;
;         const LAS float* Ra = (const LAS float*)(lds + CA_RHS) + cp * 68; const LAS float* Rb = Ra + 64 * 68;
;         float a4[4], b4[4];
; #pragma unroll
;         for (int t = 0; t < 64; ++t) {
;             f32x2_t sa = {0.f, 0.f}, sb = {0.f, 0.f};
; #pragma unroll
;             for (int p = 0; p < ((t + 3) / 4 + 1) / 2; ++p) { const f32x2_t nv = *(const LAS f32x2_t*)(Np + t * 64 + 2 * p); sa += nv * xa[p]; sb += nv * xb[p]; }
;             float ua = sa.x + sa.y, ub = sb.x + sb.y;
;             ua += dppf<0xB1>(ua); ub += dppf<0xB1>(ub); ua += dppf<0x4E>(ua); ub += dppf<0x4E>(ub);
;             const float xta = Ra[t] - ua, xtb = Rb[t] - ub;
;             if (q == (t & 3)) { if ((t >> 2) & 1) { xa[t >> 3].y = xta; xb[t >> 3].y = xtb; } else { xa[t >> 3].x = xta; xb[t >> 3].x = xtb; } }
;             a4[t & 3] = xta; b4[t & 3] = xtb;
;             if ((t & 3) == 3 && q == 0) { *(LAS u32x2*)(lds + CA_XT + cp * 144 + (t - 3) * 2) = pack4(a4[0], a4[1], a4[2], a4[3]);
;                 *(LAS u32x2*)(lds + CA_XT + (64 + cp) * 144 + (t - 3) * 2) = pack4(b4[0], b4[1], b4[2], b4[3]); }
;         }
	v_fma_f32 v44, -v48, v254, v44
	v_fma_f32 v45, -v49, v254, v45
	v_fma_f32 v46, -v50, v254, v46
	v_fma_f32 v47, -v51, v254, v47
	ds_read_b128 v[230:233], v176 offset:13616
	v_cvt_pk_bf16_f32 v252, v250, v254
	v_mov_b32_dpp v250, v43 quad_perm:[2,2,2,2] row_mask:0xf bank_mask:0xf
	s_waitcnt lgkmcnt(10)
	v_fma_f32 v42, -v54, v250, v42
	v_fma_f32 v43, -v55, v250, v43
	ds_read_b128 v[48:51], v176 offset:13872
	s_waitcnt lgkmcnt(10)
	v_fma_f32 v44, -v56, v250, v44
	v_fma_f32 v45, -v57, v250, v45
	v_fma_f32 v46, -v58, v250, v46
	v_fma_f32 v47, -v59, v250, v47
	ds_read_b128 v[52:55], v176 offset:14128
	v_mov_b32_dpp v254, v43 quad_perm:[3,3,3,3] row_mask:0xf bank_mask:0xf
	s_waitcnt lgkmcnt(10)
	v_fma_f32 v42, -v62, v254, v42
	v_fma_f32 v43, -v63, v254, v43
	ds_read_b128 v[56:59], v176 offset:14384
	s_waitcnt lgkmcnt(10)
	v_fma_f32 v44, -v64, v254, v44
	v_fma_f32 v45, -v65, v254, v45
	v_fma_f32 v46, -v66, v254, v46
	v_fma_f32 v47, -v67, v254, v47
	ds_read_b128 v[60:63], v176 offset:14640
	v_cvt_pk_bf16_f32 v253, v250, v254
	s_mov_b64 exec, s[54:55]
	ds_write_b64 v202, v[252:253] offset:88
	s_mov_b64 exec, -1
	v_mov_b32_dpp v250, v44 quad_perm:[0,0,0,0] row_mask:0xf bank_mask:0xf
	s_waitcnt lgkmcnt(11)
	v_fma_f32 v44, -v68, v250, v44
	v_fma_f32 v45, -v69, v250, v45
	v_fma_f32 v46, -v70, v250, v46
	v_fma_f32 v47, -v71, v250, v47
	ds_read_b128 v[64:67], v176 offset:14896
	v_mov_b32_dpp v254, v44 quad_perm:[1,1,1,1] row_mask:0xf bank_mask:0xf
	s_waitcnt lgkmcnt(11)
	v_fma_f32 v44, -v108, v254, v44
	v_fma_f32 v45, -v109, v254, v45
	v_fma_f32 v46, -v110, v254, v46
	v_fma_f32 v47, -v111, v254, v47
	ds_read_b128 v[68:71], v176 offset:15152
	v_cvt_pk_bf16_f32 v252, v250, v254
	v_mov_b32_dpp v250, v44 quad_perm:[2,2,2,2] row_mask:0xf bank_mask:0xf
	s_waitcnt lgkmcnt(10)
	v_fma_f32 v44, -v214, v250, v44
	v_fma_f32 v45, -v215, v250, v45
	v_fma_f32 v46, -v216, v250, v46
	v_fma_f32 v47, -v217, v250, v47
	ds_read_b128 v[108:111], v176 offset:15408
	v_mov_b32_dpp v254, v44 quad_perm:[3,3,3,3] row_mask:0xf bank_mask:0xf
	s_waitcnt lgkmcnt(10)
	v_fma_f32 v44, -v218, v254, v44
	v_fma_f32 v45, -v219, v254, v45
	v_fma_f32 v46, -v220, v254, v46
	v_fma_f32 v47, -v221, v254, v47
	ds_read_b128 v[214:217], v176 offset:15664
	v_cvt_pk_bf16_f32 v253, v250, v254
	s_mov_b64 exec, s[54:55]
	ds_write_b64 v202, v[252:253] offset:96
	s_mov_b64 exec, -1
	v_mov_b32_dpp v250, v45 quad_perm:[0,0,0,0] row_mask:0xf bank_mask:0xf
	s_waitcnt lgkmcnt(11)
	v_fma_f32 v44, -v226, v250, v44
	v_fma_f32 v45, -v227, v250, v45
	v_fma_f32 v46, -v228, v250, v46
	v_fma_f32 v47, -v229, v250, v47
	ds_read_b128 v[218:221], v176 offset:15920
	v_mov_b32_dpp v254, v45 quad_perm:[1,1,1,1] row_mask:0xf bank_mask:0xf
	s_waitcnt lgkmcnt(11)
	v_fma_f32 v44, -v230, v254, v44
	v_fma_f32 v45, -v231, v254, v45
	v_fma_f32 v46, -v232, v254, v46
	v_fma_f32 v47, -v233, v254, v47
	v_cvt_pk_bf16_f32 v252, v250, v254
	v_mov_b32_dpp v250, v45 quad_perm:[2,2,2,2] row_mask:0xf bank_mask:0xf
	s_waitcnt lgkmcnt(10)
	v_fma_f32 v44, -v48, v250, v44
	v_fma_f32 v45, -v49, v250, v45
	v_fma_f32 v46, -v50, v250, v46
	v_fma_f32 v47, -v51, v250, v47
	v_mov_b32_dpp v254, v45 quad_perm:[3,3,3,3] row_mask:0xf bank_mask:0xf
	s_waitcnt lgkmcnt(9)
	v_fma_f32 v46, -v54, v254, v46
	v_fma_f32 v47, -v55, v254, v47
	v_fma_f32 v44, -v52, v254, v44
	v_fma_f32 v45, -v53, v254, v45
	v_cvt_pk_bf16_f32 v253, v250, v254
	s_mov_b64 exec, s[54:55]
	ds_write_b64 v202, v[252:253] offset:104
	s_mov_b64 exec, -1
	v_mov_b32_dpp v250, v46 quad_perm:[0,0,0,0] row_mask:0xf bank_mask:0xf
	s_waitcnt lgkmcnt(9)
	v_fma_f32 v46, -v58, v250, v46
	v_fma_f32 v47, -v59, v250, v47
	s_nop 0
	v_mov_b32_dpp v254, v46 quad_perm:[1,1,1,1] row_mask:0xf bank_mask:0xf
	s_waitcnt lgkmcnt(8)
	v_fma_f32 v46, -v62, v254, v46
	v_fma_f32 v47, -v63, v254, v47
	v_cvt_pk_bf16_f32 v252, v250, v254
	v_mov_b32_dpp v250, v46 quad_perm:[2,2,2,2] row_mask:0xf bank_mask:0xf
	s_waitcnt lgkmcnt(6)
	v_fma_f32 v46, -v66, v250, v46
	v_fma_f32 v47, -v67, v250, v47
	s_nop 0
	v_mov_b32_dpp v254, v46 quad_perm:[3,3,3,3] row_mask:0xf bank_mask:0xf
	s_waitcnt lgkmcnt(5)
	v_fma_f32 v46, -v70, v254, v46
	v_fma_f32 v47, -v71, v254, v47
	v_cvt_pk_bf16_f32 v253, v250, v254
	s_mov_b64 exec, s[54:55]
	ds_write_b64 v202, v[252:253] offset:112
	s_mov_b64 exec, -1
	v_mov_b32_dpp v250, v47 quad_perm:[0,0,0,0] row_mask:0xf bank_mask:0xf
	s_waitcnt lgkmcnt(5)
	v_fma_f32 v46, -v110, v250, v46
	v_fma_f32 v47, -v111, v250, v47
	s_nop 1
	v_mov_b32_dpp v254, v47 quad_perm:[1,1,1,1] row_mask:0xf bank_mask:0xf
	s_waitcnt lgkmcnt(4)
	v_fma_f32 v46, -v216, v254, v46
	v_fma_f32 v47, -v217, v254, v47
	v_cvt_pk_bf16_f32 v252, v250, v254
	s_nop 0
	v_mov_b32_dpp v250, v47 quad_perm:[2,2,2,2] row_mask:0xf bank_mask:0xf
	s_waitcnt lgkmcnt(2)
	v_fma_f32 v46, -v220, v250, v46
	v_fma_f32 v47, -v221, v250, v47
	s_nop 1
	v_mov_b32_dpp v254, v47 quad_perm:[3,3,3,3] row_mask:0xf bank_mask:0xf
	v_cvt_pk_bf16_f32 v253, v250, v254
	s_mov_b64 exec, s[54:55]
	ds_write_b64 v202, v[252:253] offset:120
	s_mov_b64 exec, -1
	s_branch .LBB0_146
